# hgrn pass-C staging batched; FFN2 absmax streamed; int8 GEMM epilogues load all row scales up front
# speedup vs baseline: 1.1430x; 1.0214x over previous
.LBB0_369:
	v_lshl_or_b32 v112, s25, 8, v169
	v_ashrrev_i32_e32 v113, 31, v112
	v_lshl_add_u32 v162, s24, 8, v167
	v_readlane_b32 s64, v251, 8
	v_lshl_add_u64 v[120:121], v[112:113], 2, s[22:23]
	v_ashrrev_i32_e32 v163, 31, v162
	v_readlane_b32 s70, v251, 14
	v_readlane_b32 s71, v251, 15
	global_load_dwordx4 v[112:115], v[120:121], off
	v_cvt_f32_i32_e32 v141, v141
	v_lshl_add_u64 v[164:165], v[162:163], 2, s[70:71]
	global_load_dword v172, v[164:165], off
	global_load_dword v200, v[164:165], off offset:64
	global_load_dword v201, v[164:165], off offset:128
	global_load_dword v202, v[164:165], off offset:192
	global_load_dword v203, v[164:165], off offset:512
	global_load_dword v204, v[164:165], off offset:576
	global_load_dword v205, v[164:165], off offset:640
	global_load_dword v206, v[164:165], off offset:704
	global_load_dwordx4 v[124:127], v[120:121], off offset:512
	global_load_dwordx4 v[116:119], v[120:121], off offset:16
	s_nop 0
	global_load_dwordx4 v[120:123], v[120:121], off offset:528
	v_cvt_f32_i32_e32 v140, v140
	v_cvt_f32_i32_e32 v143, v143
	v_cvt_f32_i32_e32 v142, v142
	v_cvt_f32_i32_e32 v133, v133
	v_cvt_f32_i32_e32 v132, v132
	v_cvt_f32_i32_e32 v135, v135
	v_cvt_f32_i32_e32 v134, v134
	v_cvt_f32_i32_e32 v137, v137
	v_cvt_f32_i32_e32 v136, v136
	v_cvt_f32_i32_e32 v131, v131
	v_cvt_f32_i32_e32 v130, v130
	v_cvt_f32_i32_e32 v139, v139
	v_cvt_f32_i32_e32 v138, v138
	v_cvt_f32_i32_e32 v175, v129
	v_cvt_f32_i32_e32 v174, v128
	v_readlane_b32 s2, v251, 39
	s_lshl_b32 s24, s25, 7
	v_readlane_b32 s3, v251, 40
	s_ashr_i32 s25, s24, 31
	s_lshl_b64 s[24:25], s[24:25], 1
	v_mov_b64_e32 v[128:129], s[2:3]
	v_mad_i64_i32 v[176:177], s[2:3], v162, s54, v[128:129]
	v_lshl_add_u64 v[176:177], v[176:177], 0, s[24:25]
	v_lshl_add_u64 v[176:177], v[176:177], 0, s[8:9]
	v_lshl_add_u64 v[176:177], v[176:177], 0, v[152:153]
	v_cvt_f32_i32_e32 v109, v109
	v_cvt_f32_i32_e32 v108, v108
	v_cvt_f32_i32_e32 v111, v111
	v_cvt_f32_i32_e32 v110, v110
	v_cvt_f32_i32_e32 v101, v101
	v_cvt_f32_i32_e32 v100, v100
	v_cvt_f32_i32_e32 v103, v103
	v_cvt_f32_i32_e32 v102, v102
	v_cvt_f32_i32_e32 v105, v105
	v_cvt_f32_i32_e32 v104, v104
	v_cvt_f32_i32_e32 v99, v99
	v_cvt_f32_i32_e32 v98, v98
	v_cvt_f32_i32_e32 v107, v107
	v_cvt_f32_i32_e32 v106, v106
	v_cvt_f32_i32_e32 v97, v97
	v_cvt_f32_i32_e32 v96, v96
	v_cvt_f32_i32_e32 v93, v93
	v_cvt_f32_i32_e32 v92, v92
	v_cvt_f32_i32_e32 v95, v95
	v_cvt_f32_i32_e32 v94, v94
	v_cvt_f32_i32_e32 v85, v85
	v_cvt_f32_i32_e32 v84, v84
	v_cvt_f32_i32_e32 v87, v87
	v_cvt_f32_i32_e32 v86, v86
	v_cvt_f32_i32_e32 v89, v89
	v_cvt_f32_i32_e32 v88, v88
	v_cvt_f32_i32_e32 v83, v83
	v_cvt_f32_i32_e32 v82, v82
	v_cvt_f32_i32_e32 v91, v91
	v_cvt_f32_i32_e32 v90, v90
	v_cvt_f32_i32_e32 v81, v81
	v_cvt_f32_i32_e32 v80, v80
	v_cvt_f32_i32_e32 v77, v77
	v_cvt_f32_i32_e32 v76, v76
	v_cvt_f32_i32_e32 v79, v79
	v_cvt_f32_i32_e32 v78, v78
	v_cvt_f32_i32_e32 v69, v69
	v_cvt_f32_i32_e32 v68, v68
	v_cvt_f32_i32_e32 v71, v71
	v_cvt_f32_i32_e32 v70, v70
	v_cvt_f32_i32_e32 v73, v73
	v_cvt_f32_i32_e32 v72, v72
	v_cvt_f32_i32_e32 v67, v67
	v_cvt_f32_i32_e32 v66, v66
	v_cvt_f32_i32_e32 v75, v75
	v_cvt_f32_i32_e32 v74, v74
	v_cvt_f32_i32_e32 v65, v65
	v_cvt_f32_i32_e32 v64, v64
	v_cvt_f32_i32_e32 v61, v61
	v_cvt_f32_i32_e32 v60, v60
	s_waitcnt vmcnt(0)
	v_pk_mul_f32 v[178:179], v[112:113], v[172:173] op_sel_hi:[1,0]
	v_pk_mul_f32 v[182:183], v[114:115], v[172:173] op_sel_hi:[1,0]
	v_pk_mul_f32 v[186:187], v[116:117], v[172:173] op_sel_hi:[1,0]
	v_pk_mul_f32 v[192:193], v[118:119], v[172:173] op_sel_hi:[1,0]
	v_pk_mul_f32 v[180:181], v[124:125], v[172:173] op_sel_hi:[1,0]
	v_pk_mul_f32 v[184:185], v[126:127], v[172:173] op_sel_hi:[1,0]
	v_pk_mul_f32 v[188:189], v[120:121], v[172:173] op_sel_hi:[1,0]
	v_pk_mul_f32 v[172:173], v[122:123], v[172:173] op_sel_hi:[1,0]
	v_pk_mul_f32 v[140:141], v[178:179], v[140:141]
	v_pk_mul_f32 v[142:143], v[182:183], v[142:143]
	v_pk_mul_f32 v[132:133], v[186:187], v[132:133]
	v_pk_mul_f32 v[134:135], v[192:193], v[134:135]
	v_pk_mul_f32 v[136:137], v[180:181], v[136:137]
	v_pk_mul_f32 v[130:131], v[172:173], v[130:131]
	v_mul_f32_e32 v163, 0xbfb8aa3b, v140
	v_mul_f32_e32 v171, 0xbfb8aa3b, v141
	v_mul_f32_e32 v172, 0xbfb8aa3b, v142
	v_mul_f32_e32 v173, 0xbfb8aa3b, v143
	v_mul_f32_e32 v178, 0xbfb8aa3b, v132
	v_mul_f32_e32 v179, 0xbfb8aa3b, v133
	v_mul_f32_e32 v180, 0xbfb8aa3b, v134
	v_mul_f32_e32 v181, 0xbfb8aa3b, v135
	v_exp_f32_e32 v163, v163
	v_exp_f32_e32 v171, v171
	v_exp_f32_e32 v172, v172
	v_exp_f32_e32 v173, v173
	v_exp_f32_e32 v178, v178
	v_exp_f32_e32 v179, v179
	v_exp_f32_e32 v180, v180
	v_exp_f32_e32 v181, v181
	v_pk_mul_f32 v[138:139], v[184:185], v[138:139]
	v_add_f32_e32 v163, 1.0, v163
	v_add_f32_e32 v171, 1.0, v171
	v_add_f32_e32 v182, 1.0, v172
	v_add_f32_e32 v183, 1.0, v173
	v_add_f32_e32 v184, 1.0, v178
	v_add_f32_e32 v185, 1.0, v179
	v_add_f32_e32 v186, 1.0, v180
	v_add_f32_e32 v187, 1.0, v181
	v_rcp_f32_e32 v172, v163
	v_rcp_f32_e32 v173, v171
	v_rcp_f32_e32 v178, v182
	v_rcp_f32_e32 v179, v183
	v_rcp_f32_e32 v180, v184
	v_rcp_f32_e32 v181, v185
	v_rcp_f32_e32 v182, v186
	v_rcp_f32_e32 v183, v187
	v_pk_mul_f32 v[174:175], v[188:189], v[174:175]
	v_pk_mul_f32 v[140:141], v[140:141], v[172:173]
	v_pk_mul_f32 v[142:143], v[142:143], v[178:179]
	v_pk_mul_f32 v[132:133], v[132:133], v[180:181]
	v_pk_mul_f32 v[134:135], v[134:135], v[182:183]
	v_pk_mul_f32 v[136:137], v[136:137], v[140:141]
	v_pk_mul_f32 v[138:139], v[138:139], v[142:143]
	v_pk_mul_f32 v[132:133], v[174:175], v[132:133]
	v_pk_mul_f32 v[134:135], v[130:131], v[134:135]
	v_cvt_pk_bf16_f32 v130, v136, v137
	v_cvt_pk_bf16_f32 v131, v138, v139
	v_cvt_pk_bf16_f32 v132, v132, v133
	v_cvt_pk_bf16_f32 v133, v134, v135
	global_store_dwordx4 v[176:177], v[130:133], off
	s_nop 1
	v_mov_b32_e32 v130, v200
	v_cvt_f32_i32_e32 v63, v63
	v_or_b32_e32 v131, 16, v162
	v_mad_i64_i32 v[132:133], s[2:3], v131, s54, v[128:129]
	v_lshl_add_u64 v[132:133], v[132:133], 0, s[24:25]
	v_lshl_add_u64 v[132:133], v[132:133], 0, s[8:9]
	v_lshl_add_u64 v[132:133], v[132:133], 0, v[152:153]
	v_cvt_f32_i32_e32 v62, v62
	v_cvt_f32_i32_e32 v53, v53
	v_cvt_f32_i32_e32 v52, v52
	v_cvt_f32_i32_e32 v55, v55
	v_cvt_f32_i32_e32 v54, v54
	v_cvt_f32_i32_e32 v57, v57
	v_cvt_f32_i32_e32 v56, v56
	v_cvt_f32_i32_e32 v51, v51
	v_cvt_f32_i32_e32 v50, v50
	v_cvt_f32_i32_e32 v59, v59
	v_cvt_f32_i32_e32 v58, v58
	v_cvt_f32_i32_e32 v49, v49
	v_cvt_f32_i32_e32 v48, v48
	v_cvt_f32_i32_e32 v45, v45
	v_cvt_f32_i32_e32 v44, v44
	v_cvt_f32_i32_e32 v47, v47
	v_cvt_f32_i32_e32 v46, v46
	v_cvt_f32_i32_e32 v37, v37
	v_cvt_f32_i32_e32 v36, v36
	v_cvt_f32_i32_e32 v39, v39
	v_cvt_f32_i32_e32 v38, v38
	v_cvt_f32_i32_e32 v41, v41
	v_cvt_f32_i32_e32 v40, v40
	v_cvt_f32_i32_e32 v35, v35
	v_cvt_f32_i32_e32 v34, v34
	v_cvt_f32_i32_e32 v43, v43
	v_cvt_f32_i32_e32 v42, v42
	v_cvt_f32_i32_e32 v33, v33
	v_cvt_f32_i32_e32 v32, v32
	v_cvt_f32_i32_e32 v29, v29
	v_cvt_f32_i32_e32 v28, v28
	v_cvt_f32_i32_e32 v31, v31
	v_cvt_f32_i32_e32 v30, v30
	v_cvt_f32_i32_e32 v21, v21
	v_cvt_f32_i32_e32 v20, v20
	v_cvt_f32_i32_e32 v23, v23
	v_cvt_f32_i32_e32 v22, v22
	v_cvt_f32_i32_e32 v25, v25
	v_cvt_f32_i32_e32 v24, v24
	v_cvt_f32_i32_e32 v19, v19
	v_cvt_f32_i32_e32 v18, v18
	v_cvt_f32_i32_e32 v27, v27
	v_cvt_f32_i32_e32 v26, v26
	v_cvt_f32_i32_e32 v17, v17
	v_cvt_f32_i32_e32 v16, v16
	v_cvt_f32_i32_e32 v13, v13
	v_cvt_f32_i32_e32 v12, v12
	v_cvt_f32_i32_e32 v15, v15
	v_cvt_f32_i32_e32 v14, v14
	v_cvt_f32_i32_e32 v5, v5
	v_cvt_f32_i32_e32 v4, v4
	v_cvt_f32_i32_e32 v7, v7
	v_cvt_f32_i32_e32 v6, v6
	v_cvt_f32_i32_e32 v9, v9
	v_cvt_f32_i32_e32 v8, v8
	v_cvt_f32_i32_e32 v3, v3
	v_cvt_f32_i32_e32 v2, v2
	v_cvt_f32_i32_e32 v11, v11
	v_cvt_f32_i32_e32 v10, v10
	v_cvt_f32_i32_e32 v1, v1
	v_cvt_f32_i32_e32 v0, v0
	s_andn2_b64 vcc, exec, s[0:1]
	s_mov_b64 s[0:1], -1
	v_readlane_b32 s65, v251, 9
	v_readlane_b32 s66, v251, 10
	v_readlane_b32 s67, v251, 11
	v_readlane_b32 s68, v251, 12
	v_readlane_b32 s69, v251, 13
	v_pk_mul_f32 v[134:135], v[112:113], v[130:131] op_sel_hi:[1,0]
	v_pk_mul_f32 v[138:139], v[114:115], v[130:131] op_sel_hi:[1,0]
	v_pk_mul_f32 v[142:143], v[116:117], v[130:131] op_sel_hi:[1,0]
	v_pk_mul_f32 v[174:175], v[118:119], v[130:131] op_sel_hi:[1,0]
	v_pk_mul_f32 v[136:137], v[124:125], v[130:131] op_sel_hi:[1,0]
	v_pk_mul_f32 v[140:141], v[126:127], v[130:131] op_sel_hi:[1,0]
	v_pk_mul_f32 v[172:173], v[120:121], v[130:131] op_sel_hi:[1,0]
	v_pk_mul_f32 v[130:131], v[122:123], v[130:131] op_sel_hi:[1,0]
	v_pk_mul_f32 v[108:109], v[134:135], v[108:109]
	v_pk_mul_f32 v[110:111], v[138:139], v[110:111]
	v_pk_mul_f32 v[100:101], v[142:143], v[100:101]
	v_pk_mul_f32 v[102:103], v[174:175], v[102:103]
	v_pk_mul_f32 v[104:105], v[136:137], v[104:105]
	v_pk_mul_f32 v[98:99], v[130:131], v[98:99]
	v_mul_f32_e32 v130, 0xbfb8aa3b, v108
	v_mul_f32_e32 v131, 0xbfb8aa3b, v109
	v_mul_f32_e32 v134, 0xbfb8aa3b, v110
	v_mul_f32_e32 v135, 0xbfb8aa3b, v111
	v_mul_f32_e32 v136, 0xbfb8aa3b, v100
	v_mul_f32_e32 v137, 0xbfb8aa3b, v101
	v_mul_f32_e32 v138, 0xbfb8aa3b, v102
	v_mul_f32_e32 v139, 0xbfb8aa3b, v103
	v_exp_f32_e32 v130, v130
	v_exp_f32_e32 v131, v131
	v_exp_f32_e32 v134, v134
	v_exp_f32_e32 v135, v135
	v_exp_f32_e32 v136, v136
	v_exp_f32_e32 v137, v137
	v_exp_f32_e32 v138, v138
	v_exp_f32_e32 v139, v139
	v_add_f32_e32 v130, 1.0, v130
	v_add_f32_e32 v131, 1.0, v131
	v_add_f32_e32 v134, 1.0, v134
	v_add_f32_e32 v135, 1.0, v135
	v_add_f32_e32 v136, 1.0, v136
	v_add_f32_e32 v137, 1.0, v137
	v_add_f32_e32 v138, 1.0, v138
	v_add_f32_e32 v139, 1.0, v139
	v_rcp_f32_e32 v130, v130
	v_rcp_f32_e32 v131, v131
	v_rcp_f32_e32 v134, v134
	v_rcp_f32_e32 v135, v135
	v_rcp_f32_e32 v136, v136
	v_rcp_f32_e32 v137, v137
	v_rcp_f32_e32 v138, v138
	v_rcp_f32_e32 v139, v139
	v_pk_mul_f32 v[106:107], v[140:141], v[106:107]
	v_pk_mul_f32 v[96:97], v[172:173], v[96:97]
	v_pk_mul_f32 v[108:109], v[108:109], v[130:131]
	v_pk_mul_f32 v[110:111], v[110:111], v[134:135]
	v_pk_mul_f32 v[100:101], v[100:101], v[136:137]
	v_pk_mul_f32 v[102:103], v[102:103], v[138:139]
	v_pk_mul_f32 v[104:105], v[104:105], v[108:109]
	v_pk_mul_f32 v[106:107], v[106:107], v[110:111]
	v_pk_mul_f32 v[100:101], v[96:97], v[100:101]
	v_pk_mul_f32 v[102:103], v[98:99], v[102:103]
	v_cvt_pk_bf16_f32 v96, v104, v105
	v_cvt_pk_bf16_f32 v97, v106, v107
	v_cvt_pk_bf16_f32 v98, v100, v101
	v_cvt_pk_bf16_f32 v99, v102, v103
	global_store_dwordx4 v[132:133], v[96:99], off
	s_nop 1
	v_mov_b32_e32 v96, v201
	s_nop 0
	v_or_b32_e32 v97, 32, v162
	v_mad_i64_i32 v[98:99], s[2:3], v97, s54, v[128:129]
	v_lshl_add_u64 v[98:99], v[98:99], 0, s[24:25]
	v_lshl_add_u64 v[98:99], v[98:99], 0, s[8:9]
	v_lshl_add_u64 v[98:99], v[98:99], 0, v[152:153]
	v_pk_mul_f32 v[100:101], v[112:113], v[96:97] op_sel_hi:[1,0]
	v_pk_mul_f32 v[104:105], v[114:115], v[96:97] op_sel_hi:[1,0]
	v_pk_mul_f32 v[108:109], v[116:117], v[96:97] op_sel_hi:[1,0]
	v_pk_mul_f32 v[130:131], v[118:119], v[96:97] op_sel_hi:[1,0]
	v_pk_mul_f32 v[102:103], v[124:125], v[96:97] op_sel_hi:[1,0]
	v_pk_mul_f32 v[106:107], v[126:127], v[96:97] op_sel_hi:[1,0]
	v_pk_mul_f32 v[110:111], v[120:121], v[96:97] op_sel_hi:[1,0]
	v_pk_mul_f32 v[96:97], v[122:123], v[96:97] op_sel_hi:[1,0]
	v_pk_mul_f32 v[92:93], v[100:101], v[92:93]
	v_pk_mul_f32 v[94:95], v[104:105], v[94:95]
	v_pk_mul_f32 v[84:85], v[108:109], v[84:85]
	v_pk_mul_f32 v[86:87], v[130:131], v[86:87]
	v_pk_mul_f32 v[88:89], v[102:103], v[88:89]
	v_pk_mul_f32 v[82:83], v[96:97], v[82:83]
	v_mul_f32_e32 v96, 0xbfb8aa3b, v92
	v_mul_f32_e32 v97, 0xbfb8aa3b, v93
	v_mul_f32_e32 v100, 0xbfb8aa3b, v94
	v_mul_f32_e32 v101, 0xbfb8aa3b, v95
	v_mul_f32_e32 v102, 0xbfb8aa3b, v84
	v_mul_f32_e32 v103, 0xbfb8aa3b, v85
	v_mul_f32_e32 v104, 0xbfb8aa3b, v86
	v_mul_f32_e32 v105, 0xbfb8aa3b, v87
	v_exp_f32_e32 v96, v96
	v_exp_f32_e32 v97, v97
	v_exp_f32_e32 v100, v100
	v_exp_f32_e32 v101, v101
	v_exp_f32_e32 v102, v102
	v_exp_f32_e32 v103, v103
	v_exp_f32_e32 v104, v104
	v_exp_f32_e32 v105, v105
	v_add_f32_e32 v96, 1.0, v96
	v_add_f32_e32 v97, 1.0, v97
	v_add_f32_e32 v100, 1.0, v100
	v_add_f32_e32 v101, 1.0, v101
	v_add_f32_e32 v102, 1.0, v102
	v_add_f32_e32 v103, 1.0, v103
	v_add_f32_e32 v104, 1.0, v104
	v_add_f32_e32 v105, 1.0, v105
	v_rcp_f32_e32 v96, v96
	v_rcp_f32_e32 v97, v97
	v_rcp_f32_e32 v100, v100
	v_rcp_f32_e32 v101, v101
	v_rcp_f32_e32 v102, v102
	v_rcp_f32_e32 v103, v103
	v_rcp_f32_e32 v104, v104
	v_rcp_f32_e32 v105, v105
	v_pk_mul_f32 v[90:91], v[106:107], v[90:91]
	v_pk_mul_f32 v[80:81], v[110:111], v[80:81]
	v_pk_mul_f32 v[92:93], v[92:93], v[96:97]
	v_pk_mul_f32 v[94:95], v[94:95], v[100:101]
	v_pk_mul_f32 v[84:85], v[84:85], v[102:103]
	v_pk_mul_f32 v[86:87], v[86:87], v[104:105]
	v_pk_mul_f32 v[88:89], v[88:89], v[92:93]
	v_pk_mul_f32 v[90:91], v[90:91], v[94:95]
	v_pk_mul_f32 v[84:85], v[80:81], v[84:85]
	v_pk_mul_f32 v[86:87], v[82:83], v[86:87]
	v_cvt_pk_bf16_f32 v80, v88, v89
	v_cvt_pk_bf16_f32 v81, v90, v91
	v_cvt_pk_bf16_f32 v82, v84, v85
	v_cvt_pk_bf16_f32 v83, v86, v87
	global_store_dwordx4 v[98:99], v[80:83], off
	s_nop 1
	v_mov_b32_e32 v80, v202
	s_nop 0
	v_or_b32_e32 v81, 48, v162
	v_mad_i64_i32 v[82:83], s[2:3], v81, s54, v[128:129]
	v_lshl_add_u64 v[82:83], v[82:83], 0, s[24:25]
	v_lshl_add_u64 v[82:83], v[82:83], 0, s[8:9]
	v_lshl_add_u64 v[82:83], v[82:83], 0, v[152:153]
	v_pk_mul_f32 v[84:85], v[112:113], v[80:81] op_sel_hi:[1,0]
	v_pk_mul_f32 v[88:89], v[114:115], v[80:81] op_sel_hi:[1,0]
	v_pk_mul_f32 v[92:93], v[116:117], v[80:81] op_sel_hi:[1,0]
	v_pk_mul_f32 v[96:97], v[118:119], v[80:81] op_sel_hi:[1,0]
	v_pk_mul_f32 v[86:87], v[124:125], v[80:81] op_sel_hi:[1,0]
	v_pk_mul_f32 v[90:91], v[126:127], v[80:81] op_sel_hi:[1,0]
	v_pk_mul_f32 v[94:95], v[120:121], v[80:81] op_sel_hi:[1,0]
	v_pk_mul_f32 v[80:81], v[122:123], v[80:81] op_sel_hi:[1,0]
	v_pk_mul_f32 v[76:77], v[84:85], v[76:77]
	v_pk_mul_f32 v[78:79], v[88:89], v[78:79]
	v_pk_mul_f32 v[68:69], v[92:93], v[68:69]
	v_pk_mul_f32 v[70:71], v[96:97], v[70:71]
	v_pk_mul_f32 v[72:73], v[86:87], v[72:73]
	v_pk_mul_f32 v[66:67], v[80:81], v[66:67]
	v_mul_f32_e32 v80, 0xbfb8aa3b, v76
	v_mul_f32_e32 v81, 0xbfb8aa3b, v77
	v_mul_f32_e32 v84, 0xbfb8aa3b, v78
	v_mul_f32_e32 v85, 0xbfb8aa3b, v79
	v_mul_f32_e32 v86, 0xbfb8aa3b, v68
	v_mul_f32_e32 v87, 0xbfb8aa3b, v69
	v_mul_f32_e32 v88, 0xbfb8aa3b, v70
	v_mul_f32_e32 v89, 0xbfb8aa3b, v71
	v_exp_f32_e32 v80, v80
	v_exp_f32_e32 v81, v81
	v_exp_f32_e32 v84, v84
	v_exp_f32_e32 v85, v85
	v_exp_f32_e32 v86, v86
	v_exp_f32_e32 v87, v87
	v_exp_f32_e32 v88, v88
	v_exp_f32_e32 v89, v89
	v_add_f32_e32 v80, 1.0, v80
	v_add_f32_e32 v81, 1.0, v81
	v_add_f32_e32 v84, 1.0, v84
	v_add_f32_e32 v85, 1.0, v85
	v_add_f32_e32 v86, 1.0, v86
	v_add_f32_e32 v87, 1.0, v87
	v_add_f32_e32 v88, 1.0, v88
	v_add_f32_e32 v89, 1.0, v89
	v_rcp_f32_e32 v80, v80
	v_rcp_f32_e32 v81, v81
	v_rcp_f32_e32 v84, v84
	v_rcp_f32_e32 v85, v85
	v_rcp_f32_e32 v86, v86
	v_rcp_f32_e32 v87, v87
	v_rcp_f32_e32 v88, v88
	v_rcp_f32_e32 v89, v89
	v_pk_mul_f32 v[74:75], v[90:91], v[74:75]
	v_pk_mul_f32 v[64:65], v[94:95], v[64:65]
	v_pk_mul_f32 v[76:77], v[76:77], v[80:81]
	v_pk_mul_f32 v[78:79], v[78:79], v[84:85]
	v_pk_mul_f32 v[68:69], v[68:69], v[86:87]
	v_pk_mul_f32 v[70:71], v[70:71], v[88:89]
	v_pk_mul_f32 v[72:73], v[72:73], v[76:77]
	v_pk_mul_f32 v[74:75], v[74:75], v[78:79]
	v_pk_mul_f32 v[68:69], v[64:65], v[68:69]
	v_pk_mul_f32 v[70:71], v[66:67], v[70:71]
	v_cvt_pk_bf16_f32 v64, v72, v73
	v_cvt_pk_bf16_f32 v65, v74, v75
	v_cvt_pk_bf16_f32 v66, v68, v69
	v_cvt_pk_bf16_f32 v67, v70, v71
	global_store_dwordx4 v[82:83], v[64:67], off
	s_nop 1
	v_mov_b32_e32 v64, v203
	s_nop 0
	v_add_u32_e32 v65, 0x80, v162
	v_mad_i64_i32 v[66:67], s[2:3], v65, s54, v[128:129]
	v_lshl_add_u64 v[66:67], v[66:67], 0, s[24:25]
	v_lshl_add_u64 v[66:67], v[66:67], 0, s[8:9]
	v_lshl_add_u64 v[66:67], v[66:67], 0, v[152:153]
	v_pk_mul_f32 v[68:69], v[112:113], v[64:65] op_sel_hi:[1,0]
	v_pk_mul_f32 v[72:73], v[114:115], v[64:65] op_sel_hi:[1,0]
	v_pk_mul_f32 v[76:77], v[116:117], v[64:65] op_sel_hi:[1,0]
	v_pk_mul_f32 v[80:81], v[118:119], v[64:65] op_sel_hi:[1,0]
	v_pk_mul_f32 v[70:71], v[124:125], v[64:65] op_sel_hi:[1,0]
	v_pk_mul_f32 v[74:75], v[126:127], v[64:65] op_sel_hi:[1,0]
	v_pk_mul_f32 v[78:79], v[120:121], v[64:65] op_sel_hi:[1,0]
	v_pk_mul_f32 v[64:65], v[122:123], v[64:65] op_sel_hi:[1,0]
	v_pk_mul_f32 v[60:61], v[68:69], v[60:61]
	v_pk_mul_f32 v[62:63], v[72:73], v[62:63]
	v_pk_mul_f32 v[52:53], v[76:77], v[52:53]
	v_pk_mul_f32 v[54:55], v[80:81], v[54:55]
	v_pk_mul_f32 v[56:57], v[70:71], v[56:57]
	v_pk_mul_f32 v[50:51], v[64:65], v[50:51]
	v_mul_f32_e32 v64, 0xbfb8aa3b, v60
	v_mul_f32_e32 v65, 0xbfb8aa3b, v61
	v_mul_f32_e32 v68, 0xbfb8aa3b, v62
	v_mul_f32_e32 v69, 0xbfb8aa3b, v63
	v_mul_f32_e32 v70, 0xbfb8aa3b, v52
	v_mul_f32_e32 v71, 0xbfb8aa3b, v53
	v_mul_f32_e32 v72, 0xbfb8aa3b, v54
	v_mul_f32_e32 v73, 0xbfb8aa3b, v55
	v_exp_f32_e32 v64, v64
	v_exp_f32_e32 v65, v65
	v_exp_f32_e32 v68, v68
	v_exp_f32_e32 v69, v69
	v_exp_f32_e32 v70, v70
	v_exp_f32_e32 v71, v71
	v_exp_f32_e32 v72, v72
	v_exp_f32_e32 v73, v73
	v_add_f32_e32 v64, 1.0, v64
	v_add_f32_e32 v65, 1.0, v65
	v_add_f32_e32 v68, 1.0, v68
	v_add_f32_e32 v69, 1.0, v69
	v_add_f32_e32 v70, 1.0, v70
	v_add_f32_e32 v71, 1.0, v71
	v_add_f32_e32 v72, 1.0, v72
	v_add_f32_e32 v73, 1.0, v73
	v_rcp_f32_e32 v64, v64
	v_rcp_f32_e32 v65, v65
	v_rcp_f32_e32 v68, v68
	v_rcp_f32_e32 v69, v69
	v_rcp_f32_e32 v70, v70
	v_rcp_f32_e32 v71, v71
	v_rcp_f32_e32 v72, v72
	v_rcp_f32_e32 v73, v73
	v_pk_mul_f32 v[58:59], v[74:75], v[58:59]
	v_pk_mul_f32 v[48:49], v[78:79], v[48:49]
	v_pk_mul_f32 v[60:61], v[60:61], v[64:65]
	v_pk_mul_f32 v[62:63], v[62:63], v[68:69]
	v_pk_mul_f32 v[52:53], v[52:53], v[70:71]
	v_pk_mul_f32 v[54:55], v[54:55], v[72:73]
	v_pk_mul_f32 v[56:57], v[56:57], v[60:61]
	v_pk_mul_f32 v[58:59], v[58:59], v[62:63]
	v_pk_mul_f32 v[52:53], v[48:49], v[52:53]
	v_pk_mul_f32 v[54:55], v[50:51], v[54:55]
	v_cvt_pk_bf16_f32 v48, v56, v57
	v_cvt_pk_bf16_f32 v49, v58, v59
	v_cvt_pk_bf16_f32 v50, v52, v53
	v_cvt_pk_bf16_f32 v51, v54, v55
	global_store_dwordx4 v[66:67], v[48:51], off
	s_nop 1
	v_mov_b32_e32 v48, v204
	s_nop 0
	v_add_u32_e32 v49, 0x90, v162
	v_mad_i64_i32 v[50:51], s[2:3], v49, s54, v[128:129]
	v_lshl_add_u64 v[50:51], v[50:51], 0, s[24:25]
	v_lshl_add_u64 v[50:51], v[50:51], 0, s[8:9]
	v_lshl_add_u64 v[50:51], v[50:51], 0, v[152:153]
	v_pk_mul_f32 v[52:53], v[112:113], v[48:49] op_sel_hi:[1,0]
	v_pk_mul_f32 v[56:57], v[114:115], v[48:49] op_sel_hi:[1,0]
	v_pk_mul_f32 v[60:61], v[116:117], v[48:49] op_sel_hi:[1,0]
	v_pk_mul_f32 v[64:65], v[118:119], v[48:49] op_sel_hi:[1,0]
	v_pk_mul_f32 v[54:55], v[124:125], v[48:49] op_sel_hi:[1,0]
	v_pk_mul_f32 v[58:59], v[126:127], v[48:49] op_sel_hi:[1,0]
	v_pk_mul_f32 v[62:63], v[120:121], v[48:49] op_sel_hi:[1,0]
	v_pk_mul_f32 v[48:49], v[122:123], v[48:49] op_sel_hi:[1,0]
	v_pk_mul_f32 v[44:45], v[52:53], v[44:45]
	v_pk_mul_f32 v[46:47], v[56:57], v[46:47]
	v_pk_mul_f32 v[36:37], v[60:61], v[36:37]
	v_pk_mul_f32 v[38:39], v[64:65], v[38:39]
	v_pk_mul_f32 v[40:41], v[54:55], v[40:41]
	v_pk_mul_f32 v[34:35], v[48:49], v[34:35]
	v_mul_f32_e32 v48, 0xbfb8aa3b, v44
	v_mul_f32_e32 v49, 0xbfb8aa3b, v45
	v_mul_f32_e32 v52, 0xbfb8aa3b, v46
	v_mul_f32_e32 v53, 0xbfb8aa3b, v47
	v_mul_f32_e32 v54, 0xbfb8aa3b, v36
	v_mul_f32_e32 v55, 0xbfb8aa3b, v37
	v_mul_f32_e32 v56, 0xbfb8aa3b, v38
	v_mul_f32_e32 v57, 0xbfb8aa3b, v39
	v_exp_f32_e32 v48, v48
	v_exp_f32_e32 v49, v49
	v_exp_f32_e32 v52, v52
	v_exp_f32_e32 v53, v53
	v_exp_f32_e32 v54, v54
	v_exp_f32_e32 v55, v55
	v_exp_f32_e32 v56, v56
	v_exp_f32_e32 v57, v57
	v_add_f32_e32 v48, 1.0, v48
	v_add_f32_e32 v49, 1.0, v49
	v_add_f32_e32 v52, 1.0, v52
	v_add_f32_e32 v53, 1.0, v53
	v_add_f32_e32 v54, 1.0, v54
	v_add_f32_e32 v55, 1.0, v55
	v_add_f32_e32 v56, 1.0, v56
	v_add_f32_e32 v57, 1.0, v57
	v_rcp_f32_e32 v48, v48
	v_rcp_f32_e32 v49, v49
	v_rcp_f32_e32 v52, v52
	v_rcp_f32_e32 v53, v53
	v_rcp_f32_e32 v54, v54
	v_rcp_f32_e32 v55, v55
	v_rcp_f32_e32 v56, v56
	v_rcp_f32_e32 v57, v57
	v_pk_mul_f32 v[42:43], v[58:59], v[42:43]
	v_pk_mul_f32 v[32:33], v[62:63], v[32:33]
	v_pk_mul_f32 v[44:45], v[44:45], v[48:49]
	v_pk_mul_f32 v[46:47], v[46:47], v[52:53]
	v_pk_mul_f32 v[36:37], v[36:37], v[54:55]
	v_pk_mul_f32 v[38:39], v[38:39], v[56:57]
	v_pk_mul_f32 v[40:41], v[40:41], v[44:45]
	v_pk_mul_f32 v[42:43], v[42:43], v[46:47]
	v_pk_mul_f32 v[36:37], v[32:33], v[36:37]
	v_pk_mul_f32 v[38:39], v[34:35], v[38:39]
	v_cvt_pk_bf16_f32 v32, v40, v41
	v_cvt_pk_bf16_f32 v33, v42, v43
	v_cvt_pk_bf16_f32 v34, v36, v37
	v_cvt_pk_bf16_f32 v35, v38, v39
	global_store_dwordx4 v[50:51], v[32:35], off
	s_nop 1
	v_mov_b32_e32 v32, v205
	s_nop 0
	v_add_u32_e32 v33, 0xa0, v162
	v_mad_i64_i32 v[34:35], s[2:3], v33, s54, v[128:129]
	v_lshl_add_u64 v[34:35], v[34:35], 0, s[24:25]
	v_lshl_add_u64 v[34:35], v[34:35], 0, s[8:9]
	v_lshl_add_u64 v[34:35], v[34:35], 0, v[152:153]
	v_pk_mul_f32 v[36:37], v[112:113], v[32:33] op_sel_hi:[1,0]
	v_pk_mul_f32 v[40:41], v[114:115], v[32:33] op_sel_hi:[1,0]
	v_pk_mul_f32 v[44:45], v[116:117], v[32:33] op_sel_hi:[1,0]
	v_pk_mul_f32 v[48:49], v[118:119], v[32:33] op_sel_hi:[1,0]
	v_pk_mul_f32 v[38:39], v[124:125], v[32:33] op_sel_hi:[1,0]
	v_pk_mul_f32 v[42:43], v[126:127], v[32:33] op_sel_hi:[1,0]
	v_pk_mul_f32 v[46:47], v[120:121], v[32:33] op_sel_hi:[1,0]
	v_pk_mul_f32 v[32:33], v[122:123], v[32:33] op_sel_hi:[1,0]
	v_pk_mul_f32 v[28:29], v[36:37], v[28:29]
	v_pk_mul_f32 v[30:31], v[40:41], v[30:31]
	v_pk_mul_f32 v[20:21], v[44:45], v[20:21]
	v_pk_mul_f32 v[22:23], v[48:49], v[22:23]
	v_pk_mul_f32 v[24:25], v[38:39], v[24:25]
	v_pk_mul_f32 v[18:19], v[32:33], v[18:19]
	v_mul_f32_e32 v32, 0xbfb8aa3b, v28
	v_mul_f32_e32 v33, 0xbfb8aa3b, v29
	v_mul_f32_e32 v36, 0xbfb8aa3b, v30
	v_mul_f32_e32 v37, 0xbfb8aa3b, v31
	v_mul_f32_e32 v38, 0xbfb8aa3b, v20
	v_mul_f32_e32 v39, 0xbfb8aa3b, v21
	v_mul_f32_e32 v40, 0xbfb8aa3b, v22
	v_mul_f32_e32 v41, 0xbfb8aa3b, v23
	v_exp_f32_e32 v32, v32
	v_exp_f32_e32 v33, v33
	v_exp_f32_e32 v36, v36
	v_exp_f32_e32 v37, v37
	v_exp_f32_e32 v38, v38
	v_exp_f32_e32 v39, v39
	v_exp_f32_e32 v40, v40
	v_exp_f32_e32 v41, v41
	v_add_f32_e32 v32, 1.0, v32
	v_add_f32_e32 v33, 1.0, v33
	v_add_f32_e32 v36, 1.0, v36
	v_add_f32_e32 v37, 1.0, v37
	v_add_f32_e32 v38, 1.0, v38
	v_add_f32_e32 v39, 1.0, v39
	v_add_f32_e32 v40, 1.0, v40
	v_add_f32_e32 v41, 1.0, v41
	v_rcp_f32_e32 v32, v32
	v_rcp_f32_e32 v33, v33
	v_rcp_f32_e32 v36, v36
	v_rcp_f32_e32 v37, v37
	v_rcp_f32_e32 v38, v38
	v_rcp_f32_e32 v39, v39
	v_rcp_f32_e32 v40, v40
	v_rcp_f32_e32 v41, v41
	v_pk_mul_f32 v[26:27], v[42:43], v[26:27]
	v_pk_mul_f32 v[16:17], v[46:47], v[16:17]
	v_pk_mul_f32 v[28:29], v[28:29], v[32:33]
	v_pk_mul_f32 v[30:31], v[30:31], v[36:37]
	v_pk_mul_f32 v[20:21], v[20:21], v[38:39]
	v_pk_mul_f32 v[22:23], v[22:23], v[40:41]
	v_pk_mul_f32 v[24:25], v[24:25], v[28:29]
	v_pk_mul_f32 v[26:27], v[26:27], v[30:31]
	v_pk_mul_f32 v[20:21], v[16:17], v[20:21]
	v_pk_mul_f32 v[22:23], v[18:19], v[22:23]
	v_cvt_pk_bf16_f32 v16, v24, v25
	v_cvt_pk_bf16_f32 v17, v26, v27
	v_cvt_pk_bf16_f32 v18, v20, v21
	v_cvt_pk_bf16_f32 v19, v22, v23
	global_store_dwordx4 v[34:35], v[16:19], off
	s_nop 1
	v_mov_b32_e32 v16, v206
	s_nop 0
	v_add_u32_e32 v17, 0xb0, v162
	v_mad_i64_i32 v[18:19], s[2:3], v17, s54, v[128:129]
	v_lshl_add_u64 v[18:19], v[18:19], 0, s[24:25]
	v_lshl_add_u64 v[18:19], v[18:19], 0, s[8:9]
	v_lshl_add_u64 v[18:19], v[18:19], 0, v[152:153]
	v_pk_mul_f32 v[20:21], v[112:113], v[16:17] op_sel_hi:[1,0]
	v_pk_mul_f32 v[24:25], v[114:115], v[16:17] op_sel_hi:[1,0]
	v_pk_mul_f32 v[28:29], v[116:117], v[16:17] op_sel_hi:[1,0]
	v_pk_mul_f32 v[32:33], v[118:119], v[16:17] op_sel_hi:[1,0]
	v_pk_mul_f32 v[22:23], v[124:125], v[16:17] op_sel_hi:[1,0]
	v_pk_mul_f32 v[26:27], v[126:127], v[16:17] op_sel_hi:[1,0]
	v_pk_mul_f32 v[30:31], v[120:121], v[16:17] op_sel_hi:[1,0]
	v_pk_mul_f32 v[16:17], v[122:123], v[16:17] op_sel_hi:[1,0]
	v_pk_mul_f32 v[12:13], v[20:21], v[12:13]
	v_pk_mul_f32 v[14:15], v[24:25], v[14:15]
	v_pk_mul_f32 v[4:5], v[28:29], v[4:5]
	v_pk_mul_f32 v[6:7], v[32:33], v[6:7]
	v_pk_mul_f32 v[8:9], v[22:23], v[8:9]
	v_pk_mul_f32 v[2:3], v[16:17], v[2:3]
	v_mul_f32_e32 v16, 0xbfb8aa3b, v12
	v_mul_f32_e32 v17, 0xbfb8aa3b, v13
	v_mul_f32_e32 v20, 0xbfb8aa3b, v14
	v_mul_f32_e32 v21, 0xbfb8aa3b, v15
	v_mul_f32_e32 v22, 0xbfb8aa3b, v4
	v_mul_f32_e32 v23, 0xbfb8aa3b, v5
	v_mul_f32_e32 v24, 0xbfb8aa3b, v6
	v_mul_f32_e32 v25, 0xbfb8aa3b, v7
	v_exp_f32_e32 v16, v16
	v_exp_f32_e32 v17, v17
	v_exp_f32_e32 v20, v20
	v_exp_f32_e32 v21, v21
	v_exp_f32_e32 v22, v22
	v_exp_f32_e32 v23, v23
	v_exp_f32_e32 v24, v24
	v_exp_f32_e32 v25, v25
	v_add_f32_e32 v16, 1.0, v16
	v_add_f32_e32 v17, 1.0, v17
	v_add_f32_e32 v20, 1.0, v20
	v_add_f32_e32 v21, 1.0, v21
	v_add_f32_e32 v22, 1.0, v22
	v_add_f32_e32 v23, 1.0, v23
	v_add_f32_e32 v24, 1.0, v24
	v_add_f32_e32 v25, 1.0, v25
	v_rcp_f32_e32 v16, v16
	v_rcp_f32_e32 v17, v17
	v_rcp_f32_e32 v20, v20
	v_rcp_f32_e32 v21, v21
	v_rcp_f32_e32 v22, v22
	v_rcp_f32_e32 v23, v23
	v_rcp_f32_e32 v24, v24
	v_rcp_f32_e32 v25, v25
	v_pk_mul_f32 v[10:11], v[26:27], v[10:11]
	v_pk_mul_f32 v[0:1], v[30:31], v[0:1]
	v_pk_mul_f32 v[12:13], v[12:13], v[16:17]
	v_pk_mul_f32 v[14:15], v[14:15], v[20:21]
	v_pk_mul_f32 v[4:5], v[4:5], v[22:23]
	v_pk_mul_f32 v[6:7], v[6:7], v[24:25]
	v_pk_mul_f32 v[8:9], v[8:9], v[12:13]
	v_pk_mul_f32 v[10:11], v[10:11], v[14:15]
	v_pk_mul_f32 v[4:5], v[0:1], v[4:5]
	v_pk_mul_f32 v[6:7], v[2:3], v[6:7]
	v_cvt_pk_bf16_f32 v0, v8, v9
	v_cvt_pk_bf16_f32 v1, v10, v11
	v_cvt_pk_bf16_f32 v2, v4, v5
	v_cvt_pk_bf16_f32 v3, v6, v7
	global_store_dwordx4 v[18:19], v[0:3], off
	s_cbranch_vccnz .LBB0_361
	s_andn2_b64 vcc, exec, s[10:11]
	s_cbranch_vccnz .LBB0_360
	s_barrier
	s_branch .LBB0_360

.LBB0_1039:
	v_lshl_add_u32 v168, s12, 8, v172
	v_lshl_or_b32 v176, s13, 8, v174
	v_readlane_b32 s2, v252, 26
	v_ashrrev_i32_e32 v169, 31, v168
	v_ashrrev_i32_e32 v177, 31, v176
	v_readlane_b32 s3, v252, 27
	v_lshl_add_u64 v[170:171], v[168:169], 2, s[8:9]
	v_cvt_f32_i32_e32 v186, v92
	v_lshl_add_u64 v[178:179], v[176:177], 2, s[2:3]
	global_load_dword v169, v[170:171], off
	global_load_dword v210, v[170:171], off offset:64
	global_load_dword v211, v[170:171], off offset:128
	global_load_dword v212, v[170:171], off offset:192
	global_load_dword v213, v[170:171], off offset:512
	global_load_dword v214, v[170:171], off offset:576
	global_load_dword v215, v[170:171], off offset:640
	global_load_dword v216, v[170:171], off offset:704
	global_load_dwordx4 v[100:103], v[178:179], off
	global_load_dwordx4 v[88:91], v[178:179], off offset:16
	global_load_dwordx4 v[76:79], v[178:179], off offset:512
	v_cvt_f32_i32_e32 v187, v93
	v_cvt_f32_i32_e32 v188, v94
	v_cvt_f32_i32_e32 v189, v95
	global_load_dwordx4 v[92:95], v[178:179], off offset:528
	v_cvt_f32_i32_e32 v180, v136
	v_cvt_f32_i32_e32 v181, v137
	v_cvt_f32_i32_e32 v138, v138
	v_cvt_f32_i32_e32 v139, v139
	v_cvt_f32_i32_e32 v182, v132
	v_cvt_f32_i32_e32 v183, v133
	v_cvt_f32_i32_e32 v184, v134
	v_cvt_f32_i32_e32 v185, v135
	v_mov_b64_e32 v[132:133], s[36:37]
	s_movk_i32 s12, 0x3000
	v_mad_i64_i32 v[136:137], s[2:3], v168, s12, v[132:133]
	v_lshlrev_b64 v[134:135], 1, v[176:177]
	v_lshl_add_u64 v[176:177], v[136:137], 0, v[134:135]
	v_cvt_f32_i32_e32 v128, v128
	v_cvt_f32_i32_e32 v129, v129
	v_cvt_f32_i32_e32 v130, v130
	v_cvt_f32_i32_e32 v120, v120
	v_cvt_f32_i32_e32 v122, v122
	v_cvt_f32_i32_e32 v124, v124
	v_cvt_f32_i32_e32 v125, v125
	v_cvt_f32_i32_e32 v126, v126
	v_cvt_f32_i32_e32 v127, v127
	v_cvt_f32_i32_e32 v121, v121
	v_cvt_f32_i32_e32 v123, v123
	v_cvt_f32_i32_e32 v116, v116
	v_cvt_f32_i32_e32 v117, v117
	v_cvt_f32_i32_e32 v118, v118
	v_cvt_f32_i32_e32 v119, v119
	v_cvt_f32_i32_e32 v112, v112
	v_cvt_f32_i32_e32 v113, v113
	v_cvt_f32_i32_e32 v114, v114
	v_cvt_f32_i32_e32 v109, v109
	v_cvt_f32_i32_e32 v110, v110
	v_cvt_f32_i32_e32 v111, v111
	v_cvt_f32_i32_e32 v104, v104
	v_cvt_f32_i32_e32 v105, v105
	v_cvt_f32_i32_e32 v106, v106
	v_cvt_f32_i32_e32 v108, v108
	v_cvt_f32_i32_e32 v96, v96
	v_cvt_f32_i32_e32 v97, v97
	v_cvt_f32_i32_e32 v98, v98
	v_cvt_f32_i32_e32 v99, v99
	v_cvt_f32_i32_e32 v84, v84
	v_cvt_f32_i32_e32 v85, v85
	v_cvt_f32_i32_e32 v86, v86
	v_cvt_f32_i32_e32 v80, v80
	v_cvt_f32_i32_e32 v81, v81
	v_cvt_f32_i32_e32 v82, v82
	v_cvt_f32_i32_e32 v83, v83
	v_cvt_f32_i32_e32 v72, v72
	v_cvt_f32_i32_e32 v73, v73
	v_cvt_f32_i32_e32 v74, v74
	v_cvt_f32_i32_e32 v68, v68
	v_cvt_f32_i32_e32 v69, v69
	v_cvt_f32_i32_e32 v70, v70
	v_cvt_f32_i32_e32 v71, v71
	v_cvt_f32_i32_e32 v64, v64
	v_cvt_f32_i32_e32 v65, v65
	v_cvt_f32_i32_e32 v66, v66
	v_cvt_f32_i32_e32 v60, v60
	v_cvt_f32_i32_e32 v61, v61
	v_cvt_f32_i32_e32 v62, v62
	v_cvt_f32_i32_e32 v63, v63
	v_cvt_f32_i32_e32 v56, v56
	v_cvt_f32_i32_e32 v57, v57
	v_cvt_f32_i32_e32 v58, v58
	v_cvt_f32_i32_e32 v52, v52
	v_cvt_f32_i32_e32 v53, v53
	v_cvt_f32_i32_e32 v54, v54
	v_cvt_f32_i32_e32 v55, v55
	v_cvt_f32_i32_e32 v48, v48
	v_cvt_f32_i32_e32 v49, v49
	s_waitcnt vmcnt(0)
	v_mul_f32_e32 v136, v100, v169
	v_mul_f32_e32 v137, v101, v169
	v_mul_f32_e32 v178, v102, v169
	v_mul_f32_e32 v179, v103, v169
	v_mul_f32_e32 v200, v88, v169
	v_mul_f32_e32 v201, v89, v169
	v_mul_f32_e32 v202, v90, v169
	v_mul_f32_e32 v203, v91, v169
	v_mul_f32_e32 v136, v136, v180
	v_mul_f32_e32 v137, v137, v181
	v_mul_f32_e32 v138, v178, v138
	v_mul_f32_e32 v139, v179, v139
	v_mul_f32_e32 v178, v200, v182
	v_mul_f32_e32 v179, v201, v183
	v_mul_f32_e32 v180, v202, v184
	v_mul_f32_e32 v181, v203, v185
	v_mul_f32_e32 v136, 0xbfb8aa3b, v136
	v_mul_f32_e32 v137, 0xbfb8aa3b, v137
	v_mul_f32_e32 v138, 0xbfb8aa3b, v138
	v_mul_f32_e32 v139, 0xbfb8aa3b, v139
	v_mul_f32_e32 v178, 0xbfb8aa3b, v178
	v_mul_f32_e32 v179, 0xbfb8aa3b, v179
	v_mul_f32_e32 v180, 0xbfb8aa3b, v180
	v_mul_f32_e32 v181, 0xbfb8aa3b, v181
	v_exp_f32_e32 v136, v136
	v_exp_f32_e32 v137, v137
	v_exp_f32_e32 v138, v138
	v_exp_f32_e32 v139, v139
	v_exp_f32_e32 v178, v178
	v_exp_f32_e32 v179, v179
	v_exp_f32_e32 v180, v180
	v_exp_f32_e32 v181, v181
	v_add_f32_e32 v136, 1.0, v136
	v_add_f32_e32 v137, 1.0, v137
	v_add_f32_e32 v138, 1.0, v138
	v_add_f32_e32 v139, 1.0, v139
	v_add_f32_e32 v178, 1.0, v178
	v_add_f32_e32 v179, 1.0, v179
	v_add_f32_e32 v180, 1.0, v180
	v_add_f32_e32 v181, 1.0, v181
	v_rcp_f32_e32 v136, v136
	v_rcp_f32_e32 v137, v137
	v_rcp_f32_e32 v138, v138
	v_rcp_f32_e32 v139, v139
	v_rcp_f32_e32 v178, v178
	v_rcp_f32_e32 v179, v179
	v_rcp_f32_e32 v180, v180
	v_rcp_f32_e32 v181, v181
	v_cvt_pk_bf16_f32 v136, v136, v137
	v_cvt_pk_bf16_f32 v137, v138, v139
	v_cvt_pk_bf16_f32 v138, v178, v179
	v_cvt_pk_bf16_f32 v139, v180, v181
	global_store_dwordx4 v[176:177], v[136:139], off
	v_mul_f32_e32 v204, v76, v169
	v_mul_f32_e32 v205, v77, v169
	v_mul_f32_e32 v138, v92, v169
	v_mul_f32_e32 v128, v138, v128
	v_mul_f32_e32 v138, v93, v169
	v_mul_f32_e32 v128, 0xbfb8aa3b, v128
	v_mul_f32_e32 v129, v138, v129
	v_exp_f32_e32 v128, v128
	v_mul_f32_e32 v129, 0xbfb8aa3b, v129
	v_exp_f32_e32 v129, v129
	v_mul_f32_e32 v206, v78, v169
	v_add_f32_e32 v128, 1.0, v128
	v_rcp_f32_e32 v138, v128
	v_add_f32_e32 v128, 1.0, v129
	v_mul_f32_e32 v129, v94, v169
	v_mul_f32_e32 v129, v129, v130
	v_cvt_f32_i32_e32 v130, v131
	v_mul_f32_e32 v136, v79, v169
	v_mul_f32_e32 v131, v95, v169
	v_mul_f32_e32 v182, v204, v186
	v_mul_f32_e32 v183, v205, v187
	v_mul_f32_e32 v184, v206, v188
	v_mul_f32_e32 v136, v136, v189
	v_mul_f32_e32 v129, 0xbfb8aa3b, v129
	v_mul_f32_e32 v130, v131, v130
	v_mul_f32_e32 v182, 0xbfb8aa3b, v182
	v_mul_f32_e32 v183, 0xbfb8aa3b, v183
	v_mul_f32_e32 v184, 0xbfb8aa3b, v184
	v_mul_f32_e32 v136, 0xbfb8aa3b, v136
	v_exp_f32_e32 v129, v129
	v_mul_f32_e32 v130, 0xbfb8aa3b, v130
	v_exp_f32_e32 v182, v182
	v_exp_f32_e32 v183, v183
	v_exp_f32_e32 v184, v184
	v_exp_f32_e32 v136, v136
	v_exp_f32_e32 v130, v130
	v_rcp_f32_e32 v131, v128
	v_add_f32_e32 v128, 1.0, v129
	v_add_f32_e32 v182, 1.0, v182
	v_add_f32_e32 v183, 1.0, v183
	v_add_f32_e32 v137, 1.0, v184
	v_add_f32_e32 v136, 1.0, v136
	v_rcp_f32_e32 v139, v128
	v_add_f32_e32 v128, 1.0, v130
	v_rcp_f32_e32 v182, v182
	v_rcp_f32_e32 v183, v183
	v_rcp_f32_e32 v137, v137
	v_rcp_f32_e32 v136, v136
	v_rcp_f32_e32 v169, v128
	v_cvt_pk_bf16_f32 v128, v182, v183
	v_cvt_pk_bf16_f32 v130, v138, v131
	v_cvt_pk_bf16_f32 v129, v137, v136
	v_cvt_pk_bf16_f32 v131, v139, v169
	global_store_dwordx4 v[176:177], v[128:131], off offset:256
	s_nop 1
	v_mov_b32_e32 v128, v210
	v_cvt_f32_i32_e32 v50, v50
	v_or_b32_e32 v129, 16, v168
	v_cvt_f32_i32_e32 v44, v44
	v_cvt_f32_i32_e32 v45, v45
	v_cvt_f32_i32_e32 v46, v46
	v_cvt_f32_i32_e32 v47, v47
	v_cvt_f32_i32_e32 v40, v40
	v_cvt_f32_i32_e32 v41, v41
	v_cvt_f32_i32_e32 v42, v42
	v_cvt_f32_i32_e32 v36, v36
	v_cvt_f32_i32_e32 v37, v37
	v_cvt_f32_i32_e32 v38, v38
	v_cvt_f32_i32_e32 v39, v39
	v_cvt_f32_i32_e32 v32, v32
	v_cvt_f32_i32_e32 v33, v33
	v_cvt_f32_i32_e32 v34, v34
	v_cvt_f32_i32_e32 v28, v28
	v_cvt_f32_i32_e32 v29, v29
	v_cvt_f32_i32_e32 v30, v30
	v_cvt_f32_i32_e32 v31, v31
	v_cvt_f32_i32_e32 v24, v24
	v_cvt_f32_i32_e32 v25, v25
	v_cvt_f32_i32_e32 v26, v26
	v_cvt_f32_i32_e32 v20, v20
	v_cvt_f32_i32_e32 v21, v21
	v_cvt_f32_i32_e32 v22, v22
	v_cvt_f32_i32_e32 v23, v23
	v_cvt_f32_i32_e32 v16, v16
	v_cvt_f32_i32_e32 v17, v17
	v_cvt_f32_i32_e32 v18, v18
	v_cvt_f32_i32_e32 v12, v12
	v_cvt_f32_i32_e32 v13, v13
	v_cvt_f32_i32_e32 v14, v14
	v_cvt_f32_i32_e32 v15, v15
	v_cvt_f32_i32_e32 v8, v8
	v_cvt_f32_i32_e32 v9, v9
	v_cvt_f32_i32_e32 v10, v10
	v_cvt_f32_i32_e32 v4, v4
	v_cvt_f32_i32_e32 v5, v5
	v_cvt_f32_i32_e32 v6, v6
	v_cvt_f32_i32_e32 v7, v7
	v_cvt_f32_i32_e32 v0, v0
	v_cvt_f32_i32_e32 v1, v1
	v_cvt_f32_i32_e32 v2, v2
	s_andn2_b64 vcc, exec, s[0:1]
	s_mov_b64 s[0:1], -1
	v_mul_f32_e32 v138, v88, v128
	v_mul_f32_e32 v120, v138, v120
	v_mul_f32_e32 v120, 0xbfb8aa3b, v120
	v_exp_f32_e32 v120, v120
	v_mul_f32_e32 v169, v90, v128
	v_mul_f32_e32 v122, v169, v122
	v_mul_f32_e32 v130, v100, v128
	v_mul_f32_e32 v131, v101, v128
	v_mul_f32_e32 v122, 0xbfb8aa3b, v122
	v_add_f32_e32 v120, 1.0, v120
	v_mul_f32_e32 v136, v102, v128
	v_mul_f32_e32 v137, v103, v128
	v_mul_f32_e32 v139, v89, v128
	v_mul_f32_e32 v124, v130, v124
	v_mul_f32_e32 v125, v131, v125
	v_rcp_f32_e32 v130, v120
	v_exp_f32_e32 v120, v122
	v_mul_f32_e32 v122, v91, v128
	v_mul_f32_e32 v126, v136, v126
	v_mul_f32_e32 v127, v137, v127
	v_mul_f32_e32 v121, v139, v121
	v_mul_f32_e32 v124, 0xbfb8aa3b, v124
	v_mul_f32_e32 v125, 0xbfb8aa3b, v125
	v_mul_f32_e32 v122, v122, v123
	v_mul_f32_e32 v126, 0xbfb8aa3b, v126
	v_mul_f32_e32 v127, 0xbfb8aa3b, v127
	v_mul_f32_e32 v121, 0xbfb8aa3b, v121
	v_exp_f32_e32 v124, v124
	v_exp_f32_e32 v125, v125
	v_mul_f32_e32 v122, 0xbfb8aa3b, v122
	v_exp_f32_e32 v126, v126
	v_exp_f32_e32 v127, v127
	v_exp_f32_e32 v121, v121
	v_exp_f32_e32 v122, v122
	v_add_f32_e32 v124, 1.0, v124
	v_add_f32_e32 v125, 1.0, v125
	v_add_f32_e32 v120, 1.0, v120
	v_add_f32_e32 v126, 1.0, v126
	v_add_f32_e32 v127, 1.0, v127
	v_add_f32_e32 v121, 1.0, v121
	v_rcp_f32_e32 v124, v124
	v_rcp_f32_e32 v125, v125
	v_rcp_f32_e32 v131, v120
	v_add_f32_e32 v120, 1.0, v122
	v_rcp_f32_e32 v126, v126
	v_rcp_f32_e32 v127, v127
	v_rcp_f32_e32 v123, v121
	v_rcp_f32_e32 v136, v120
	v_cvt_pk_bf16_f32 v120, v124, v125
	v_mad_i64_i32 v[124:125], s[2:3], v129, s12, v[132:133]
	v_cvt_pk_bf16_f32 v121, v126, v127
	v_cvt_pk_bf16_f32 v122, v130, v123
	v_cvt_pk_bf16_f32 v123, v131, v136
	v_lshl_add_u64 v[124:125], v[124:125], 0, v[134:135]
	global_store_dwordx4 v[124:125], v[120:123], off
	s_nop 1
	v_mul_f32_e32 v120, v76, v128
	v_mul_f32_e32 v116, v120, v116
	v_mul_f32_e32 v120, v77, v128
	v_mul_f32_e32 v117, v120, v117
	v_mul_f32_e32 v120, v78, v128
	v_mul_f32_e32 v118, v120, v118
	v_mul_f32_e32 v120, v79, v128
	v_mul_f32_e32 v119, v120, v119
	v_mul_f32_e32 v120, v92, v128
	v_mul_f32_e32 v112, v120, v112
	v_mul_f32_e32 v120, v93, v128
	v_mul_f32_e32 v112, 0xbfb8aa3b, v112
	v_mul_f32_e32 v113, v120, v113
	v_exp_f32_e32 v112, v112
	v_mul_f32_e32 v113, 0xbfb8aa3b, v113
	v_exp_f32_e32 v113, v113
	v_mul_f32_e32 v116, 0xbfb8aa3b, v116
	v_add_f32_e32 v112, 1.0, v112
	v_rcp_f32_e32 v120, v112
	v_add_f32_e32 v112, 1.0, v113
	v_mul_f32_e32 v113, v94, v128
	v_mul_f32_e32 v113, v113, v114
	v_cvt_f32_i32_e32 v114, v115
	v_mul_f32_e32 v115, v95, v128
	v_mul_f32_e32 v113, 0xbfb8aa3b, v113
	v_mul_f32_e32 v117, 0xbfb8aa3b, v117
	v_mul_f32_e32 v114, v115, v114
	v_mul_f32_e32 v118, 0xbfb8aa3b, v118
	v_mul_f32_e32 v119, 0xbfb8aa3b, v119
	v_exp_f32_e32 v113, v113
	v_mul_f32_e32 v114, 0xbfb8aa3b, v114
	v_exp_f32_e32 v116, v116
	v_exp_f32_e32 v117, v117
	v_exp_f32_e32 v118, v118
	v_exp_f32_e32 v119, v119
	v_exp_f32_e32 v114, v114
	v_rcp_f32_e32 v115, v112
	v_add_f32_e32 v112, 1.0, v113
	v_add_f32_e32 v116, 1.0, v116
	v_add_f32_e32 v117, 1.0, v117
	v_add_f32_e32 v118, 1.0, v118
	v_add_f32_e32 v119, 1.0, v119
	v_rcp_f32_e32 v121, v112
	v_add_f32_e32 v112, 1.0, v114
	v_rcp_f32_e32 v116, v116
	v_rcp_f32_e32 v117, v117
	v_rcp_f32_e32 v118, v118
	v_rcp_f32_e32 v119, v119
	v_rcp_f32_e32 v122, v112
	v_cvt_pk_bf16_f32 v112, v116, v117
	v_cvt_pk_bf16_f32 v114, v120, v115
	v_cvt_pk_bf16_f32 v113, v118, v119
	v_cvt_pk_bf16_f32 v115, v121, v122
	global_store_dwordx4 v[124:125], v[112:115], off offset:256
	s_nop 1
	v_mov_b32_e32 v112, v211
	v_mul_f32_e32 v114, v101, v112
	v_mul_f32_e32 v109, v114, v109
	v_mul_f32_e32 v114, v102, v112
	v_mul_f32_e32 v110, v114, v110
	v_mul_f32_e32 v114, v103, v112
	v_mul_f32_e32 v111, v114, v111
	v_mul_f32_e32 v114, v88, v112
	v_mul_f32_e32 v104, v114, v104
	v_mul_f32_e32 v114, v89, v112
	v_mul_f32_e32 v104, 0xbfb8aa3b, v104
	v_mul_f32_e32 v105, v114, v105
	v_exp_f32_e32 v104, v104
	v_mul_f32_e32 v105, 0xbfb8aa3b, v105
	v_exp_f32_e32 v105, v105
	v_mul_f32_e32 v113, v100, v112
	v_add_f32_e32 v104, 1.0, v104
	v_rcp_f32_e32 v114, v104
	v_add_f32_e32 v104, 1.0, v105
	v_mul_f32_e32 v105, v90, v112
	v_mul_f32_e32 v105, v105, v106
	v_cvt_f32_i32_e32 v106, v107
	v_mul_f32_e32 v108, v113, v108
	v_mul_f32_e32 v107, v91, v112
	v_mul_f32_e32 v108, 0xbfb8aa3b, v108
	v_mul_f32_e32 v109, 0xbfb8aa3b, v109
	v_mul_f32_e32 v105, 0xbfb8aa3b, v105
	v_mul_f32_e32 v106, v107, v106
	v_exp_f32_e32 v108, v108
	v_exp_f32_e32 v109, v109
	v_mul_f32_e32 v110, 0xbfb8aa3b, v110
	v_mul_f32_e32 v111, 0xbfb8aa3b, v111
	v_exp_f32_e32 v105, v105
	v_mul_f32_e32 v106, 0xbfb8aa3b, v106
	v_exp_f32_e32 v110, v110
	v_exp_f32_e32 v111, v111
	v_exp_f32_e32 v106, v106
	v_add_f32_e32 v108, 1.0, v108
	v_add_f32_e32 v109, 1.0, v109
	v_rcp_f32_e32 v107, v104
	v_add_f32_e32 v104, 1.0, v105
	v_rcp_f32_e32 v108, v108
	v_rcp_f32_e32 v109, v109
	v_add_f32_e32 v110, 1.0, v110
	v_add_f32_e32 v111, 1.0, v111
	v_rcp_f32_e32 v115, v104
	v_add_f32_e32 v104, 1.0, v106
	v_rcp_f32_e32 v110, v110
	v_rcp_f32_e32 v111, v111
	v_rcp_f32_e32 v116, v104
	v_or_b32_e32 v113, 32, v168
	v_cvt_pk_bf16_f32 v104, v108, v109
	v_mad_i64_i32 v[108:109], s[2:3], v113, s12, v[132:133]
	v_cvt_pk_bf16_f32 v105, v110, v111
	v_cvt_pk_bf16_f32 v106, v114, v107
	v_cvt_pk_bf16_f32 v107, v115, v116
	v_lshl_add_u64 v[108:109], v[108:109], 0, v[134:135]
	global_store_dwordx4 v[108:109], v[104:107], off
	s_nop 1
	v_mul_f32_e32 v104, v76, v112
	v_mul_f32_e32 v96, v104, v96
	v_mul_f32_e32 v104, v77, v112
	v_mul_f32_e32 v97, v104, v97
	v_mul_f32_e32 v104, v78, v112
	v_mul_f32_e32 v98, v104, v98
	v_mul_f32_e32 v104, v79, v112
	v_mul_f32_e32 v99, v104, v99
	v_mul_f32_e32 v104, v92, v112
	v_mul_f32_e32 v84, v104, v84
	v_mul_f32_e32 v104, v93, v112
	v_mul_f32_e32 v84, 0xbfb8aa3b, v84
	v_mul_f32_e32 v85, v104, v85
	v_exp_f32_e32 v84, v84
	v_mul_f32_e32 v85, 0xbfb8aa3b, v85
	v_exp_f32_e32 v85, v85
	v_mul_f32_e32 v96, 0xbfb8aa3b, v96
	v_add_f32_e32 v84, 1.0, v84
	v_rcp_f32_e32 v104, v84
	v_add_f32_e32 v84, 1.0, v85
	v_mul_f32_e32 v85, v94, v112
	v_mul_f32_e32 v85, v85, v86
	v_cvt_f32_i32_e32 v86, v87
	v_mul_f32_e32 v87, v95, v112
	v_mul_f32_e32 v85, 0xbfb8aa3b, v85
	v_mul_f32_e32 v97, 0xbfb8aa3b, v97
	v_mul_f32_e32 v86, v87, v86
	v_mul_f32_e32 v98, 0xbfb8aa3b, v98
	v_mul_f32_e32 v99, 0xbfb8aa3b, v99
	v_exp_f32_e32 v85, v85
	v_mul_f32_e32 v86, 0xbfb8aa3b, v86
	v_exp_f32_e32 v96, v96
	v_exp_f32_e32 v97, v97
	v_exp_f32_e32 v98, v98
	v_exp_f32_e32 v99, v99
	v_exp_f32_e32 v86, v86
	v_rcp_f32_e32 v87, v84
	v_add_f32_e32 v84, 1.0, v85
	v_add_f32_e32 v96, 1.0, v96
	v_add_f32_e32 v97, 1.0, v97
	v_add_f32_e32 v98, 1.0, v98
	v_add_f32_e32 v99, 1.0, v99
	v_rcp_f32_e32 v105, v84
	v_add_f32_e32 v84, 1.0, v86
	v_rcp_f32_e32 v96, v96
	v_rcp_f32_e32 v97, v97
	v_rcp_f32_e32 v98, v98
	v_rcp_f32_e32 v99, v99
	v_rcp_f32_e32 v106, v84
	v_cvt_pk_bf16_f32 v84, v96, v97
	v_cvt_pk_bf16_f32 v86, v104, v87
	v_cvt_pk_bf16_f32 v85, v98, v99
	v_cvt_pk_bf16_f32 v87, v105, v106
	global_store_dwordx4 v[108:109], v[84:87], off offset:256
	s_nop 1
	v_mov_b32_e32 v84, v212
	s_nop 0
	v_or_b32_e32 v85, 48, v168
	v_mul_f32_e32 v86, v100, v84
	v_mul_f32_e32 v80, v86, v80
	v_mul_f32_e32 v86, v101, v84
	v_mul_f32_e32 v81, v86, v81
	v_mul_f32_e32 v86, v102, v84
	v_mul_f32_e32 v82, v86, v82
	v_mul_f32_e32 v86, v103, v84
	v_mul_f32_e32 v83, v86, v83
	v_mul_f32_e32 v86, v88, v84
	v_mul_f32_e32 v72, v86, v72
	v_mul_f32_e32 v86, v89, v84
	v_mul_f32_e32 v72, 0xbfb8aa3b, v72
	v_mul_f32_e32 v73, v86, v73
	v_exp_f32_e32 v72, v72
	v_mul_f32_e32 v73, 0xbfb8aa3b, v73
	v_exp_f32_e32 v73, v73
	v_mul_f32_e32 v80, 0xbfb8aa3b, v80
	v_add_f32_e32 v72, 1.0, v72
	v_rcp_f32_e32 v86, v72
	v_add_f32_e32 v72, 1.0, v73
	v_mul_f32_e32 v73, v90, v84
	v_mul_f32_e32 v73, v73, v74
	v_cvt_f32_i32_e32 v74, v75
	v_mul_f32_e32 v75, v91, v84
	v_mul_f32_e32 v81, 0xbfb8aa3b, v81
	v_mul_f32_e32 v73, 0xbfb8aa3b, v73
	v_mul_f32_e32 v74, v75, v74
	v_exp_f32_e32 v80, v80
	v_exp_f32_e32 v81, v81
	v_mul_f32_e32 v82, 0xbfb8aa3b, v82
	v_mul_f32_e32 v83, 0xbfb8aa3b, v83
	v_exp_f32_e32 v73, v73
	v_mul_f32_e32 v74, 0xbfb8aa3b, v74
	v_exp_f32_e32 v82, v82
	v_exp_f32_e32 v83, v83
	v_exp_f32_e32 v74, v74
	v_add_f32_e32 v80, 1.0, v80
	v_add_f32_e32 v81, 1.0, v81
	v_rcp_f32_e32 v75, v72
	v_add_f32_e32 v72, 1.0, v73
	v_rcp_f32_e32 v80, v80
	v_rcp_f32_e32 v81, v81
	v_add_f32_e32 v82, 1.0, v82
	v_add_f32_e32 v83, 1.0, v83
	v_rcp_f32_e32 v87, v72
	v_add_f32_e32 v72, 1.0, v74
	v_rcp_f32_e32 v82, v82
	v_rcp_f32_e32 v83, v83
	v_rcp_f32_e32 v96, v72
	v_cvt_pk_bf16_f32 v72, v80, v81
	v_mad_i64_i32 v[80:81], s[2:3], v85, s12, v[132:133]
	v_cvt_pk_bf16_f32 v73, v82, v83
	v_cvt_pk_bf16_f32 v74, v86, v75
	v_cvt_pk_bf16_f32 v75, v87, v96
	v_lshl_add_u64 v[80:81], v[80:81], 0, v[134:135]
	global_store_dwordx4 v[80:81], v[72:75], off
	s_nop 1
	v_mul_f32_e32 v72, v76, v84
	v_mul_f32_e32 v68, v72, v68
	v_mul_f32_e32 v72, v77, v84
	v_mul_f32_e32 v69, v72, v69
	v_mul_f32_e32 v72, v78, v84
	v_mul_f32_e32 v70, v72, v70
	v_mul_f32_e32 v72, v79, v84
	v_mul_f32_e32 v71, v72, v71
	v_mul_f32_e32 v72, v92, v84
	v_mul_f32_e32 v64, v72, v64
	v_mul_f32_e32 v72, v93, v84
	v_mul_f32_e32 v64, 0xbfb8aa3b, v64
	v_mul_f32_e32 v65, v72, v65
	v_exp_f32_e32 v64, v64
	v_mul_f32_e32 v65, 0xbfb8aa3b, v65
	v_exp_f32_e32 v65, v65
	v_mul_f32_e32 v68, 0xbfb8aa3b, v68
	v_add_f32_e32 v64, 1.0, v64
	v_rcp_f32_e32 v72, v64
	v_add_f32_e32 v64, 1.0, v65
	v_mul_f32_e32 v65, v94, v84
	v_mul_f32_e32 v65, v65, v66
	v_cvt_f32_i32_e32 v66, v67
	v_mul_f32_e32 v67, v95, v84
	v_mul_f32_e32 v65, 0xbfb8aa3b, v65
	v_mul_f32_e32 v69, 0xbfb8aa3b, v69
	v_mul_f32_e32 v66, v67, v66
	v_mul_f32_e32 v70, 0xbfb8aa3b, v70
	v_mul_f32_e32 v71, 0xbfb8aa3b, v71
	v_exp_f32_e32 v65, v65
	v_mul_f32_e32 v66, 0xbfb8aa3b, v66
	v_exp_f32_e32 v68, v68
	v_exp_f32_e32 v69, v69
	v_exp_f32_e32 v70, v70
	v_exp_f32_e32 v71, v71
	v_exp_f32_e32 v66, v66
	v_rcp_f32_e32 v67, v64
	v_add_f32_e32 v64, 1.0, v65
	v_add_f32_e32 v68, 1.0, v68
	v_add_f32_e32 v69, 1.0, v69
	v_add_f32_e32 v70, 1.0, v70
	v_add_f32_e32 v71, 1.0, v71
	v_rcp_f32_e32 v73, v64
	v_add_f32_e32 v64, 1.0, v66
	v_rcp_f32_e32 v68, v68
	v_rcp_f32_e32 v69, v69
	v_rcp_f32_e32 v70, v70
	v_rcp_f32_e32 v71, v71
	v_rcp_f32_e32 v74, v64
	v_cvt_pk_bf16_f32 v64, v68, v69
	v_cvt_pk_bf16_f32 v66, v72, v67
	v_cvt_pk_bf16_f32 v65, v70, v71
	v_cvt_pk_bf16_f32 v67, v73, v74
	global_store_dwordx4 v[80:81], v[64:67], off offset:256
	s_nop 1
	v_mov_b32_e32 v64, v213
	s_nop 0
	v_add_u32_e32 v65, 0x80, v168
	v_mul_f32_e32 v66, v100, v64
	v_mul_f32_e32 v60, v66, v60
	v_mul_f32_e32 v66, v101, v64
	v_mul_f32_e32 v61, v66, v61
	v_mul_f32_e32 v66, v102, v64
	v_mul_f32_e32 v62, v66, v62
	v_mul_f32_e32 v66, v103, v64
	v_mul_f32_e32 v63, v66, v63
	v_mul_f32_e32 v66, v88, v64
	v_mul_f32_e32 v56, v66, v56
	v_mul_f32_e32 v66, v89, v64
	v_mul_f32_e32 v56, 0xbfb8aa3b, v56
	v_mul_f32_e32 v57, v66, v57
	v_exp_f32_e32 v56, v56
	v_mul_f32_e32 v57, 0xbfb8aa3b, v57
	v_exp_f32_e32 v57, v57
	v_mul_f32_e32 v60, 0xbfb8aa3b, v60
	v_add_f32_e32 v56, 1.0, v56
	v_rcp_f32_e32 v66, v56
	v_add_f32_e32 v56, 1.0, v57
	v_mul_f32_e32 v57, v90, v64
	v_mul_f32_e32 v57, v57, v58
	v_cvt_f32_i32_e32 v58, v59
	v_mul_f32_e32 v59, v91, v64
	v_mul_f32_e32 v61, 0xbfb8aa3b, v61
	v_mul_f32_e32 v57, 0xbfb8aa3b, v57
	v_mul_f32_e32 v58, v59, v58
	v_exp_f32_e32 v60, v60
	v_exp_f32_e32 v61, v61
	v_mul_f32_e32 v62, 0xbfb8aa3b, v62
	v_mul_f32_e32 v63, 0xbfb8aa3b, v63
	v_exp_f32_e32 v57, v57
	v_mul_f32_e32 v58, 0xbfb8aa3b, v58
	v_exp_f32_e32 v62, v62
	v_exp_f32_e32 v63, v63
	v_exp_f32_e32 v58, v58
	v_add_f32_e32 v60, 1.0, v60
	v_add_f32_e32 v61, 1.0, v61
	v_rcp_f32_e32 v59, v56
	v_add_f32_e32 v56, 1.0, v57
	v_rcp_f32_e32 v60, v60
	v_rcp_f32_e32 v61, v61
	v_add_f32_e32 v62, 1.0, v62
	v_add_f32_e32 v63, 1.0, v63
	v_rcp_f32_e32 v67, v56
	v_add_f32_e32 v56, 1.0, v58
	v_rcp_f32_e32 v62, v62
	v_rcp_f32_e32 v63, v63
	v_rcp_f32_e32 v68, v56
	v_cvt_pk_bf16_f32 v56, v60, v61
	v_mad_i64_i32 v[60:61], s[2:3], v65, s12, v[132:133]
	v_cvt_pk_bf16_f32 v57, v62, v63
	v_cvt_pk_bf16_f32 v58, v66, v59
	v_cvt_pk_bf16_f32 v59, v67, v68
	v_lshl_add_u64 v[60:61], v[60:61], 0, v[134:135]
	global_store_dwordx4 v[60:61], v[56:59], off
	s_nop 1
	v_mul_f32_e32 v56, v76, v64
	v_mul_f32_e32 v52, v56, v52
	v_mul_f32_e32 v56, v77, v64
	v_mul_f32_e32 v53, v56, v53
	v_mul_f32_e32 v56, v78, v64
	v_mul_f32_e32 v54, v56, v54
	v_mul_f32_e32 v56, v79, v64
	v_mul_f32_e32 v55, v56, v55
	v_mul_f32_e32 v56, v92, v64
	v_mul_f32_e32 v48, v56, v48
	v_mul_f32_e32 v56, v93, v64
	v_mul_f32_e32 v48, 0xbfb8aa3b, v48
	v_mul_f32_e32 v49, v56, v49
	v_exp_f32_e32 v48, v48
	v_mul_f32_e32 v49, 0xbfb8aa3b, v49
	v_exp_f32_e32 v49, v49
	v_mul_f32_e32 v52, 0xbfb8aa3b, v52
	v_add_f32_e32 v48, 1.0, v48
	v_rcp_f32_e32 v56, v48
	v_add_f32_e32 v48, 1.0, v49
	v_mul_f32_e32 v49, v94, v64
	v_mul_f32_e32 v49, v49, v50
	v_cvt_f32_i32_e32 v50, v51
	v_mul_f32_e32 v51, v95, v64
	v_mul_f32_e32 v49, 0xbfb8aa3b, v49
	v_mul_f32_e32 v53, 0xbfb8aa3b, v53
	v_mul_f32_e32 v50, v51, v50
	v_mul_f32_e32 v54, 0xbfb8aa3b, v54
	v_mul_f32_e32 v55, 0xbfb8aa3b, v55
	v_exp_f32_e32 v49, v49
	v_mul_f32_e32 v50, 0xbfb8aa3b, v50
	v_exp_f32_e32 v52, v52
	v_exp_f32_e32 v53, v53
	v_exp_f32_e32 v54, v54
	v_exp_f32_e32 v55, v55
	v_exp_f32_e32 v50, v50
	v_rcp_f32_e32 v51, v48
	v_add_f32_e32 v48, 1.0, v49
	v_add_f32_e32 v52, 1.0, v52
	v_add_f32_e32 v53, 1.0, v53
	v_add_f32_e32 v54, 1.0, v54
	v_add_f32_e32 v55, 1.0, v55
	v_rcp_f32_e32 v57, v48
	v_add_f32_e32 v48, 1.0, v50
	v_rcp_f32_e32 v52, v52
	v_rcp_f32_e32 v53, v53
	v_rcp_f32_e32 v54, v54
	v_rcp_f32_e32 v55, v55
	v_rcp_f32_e32 v58, v48
	v_cvt_pk_bf16_f32 v48, v52, v53
	v_cvt_pk_bf16_f32 v50, v56, v51
	v_cvt_pk_bf16_f32 v49, v54, v55
	v_cvt_pk_bf16_f32 v51, v57, v58
	global_store_dwordx4 v[60:61], v[48:51], off offset:256
	s_nop 1
	v_mov_b32_e32 v48, v214
	s_nop 0
	v_add_u32_e32 v49, 0x90, v168
	v_mul_f32_e32 v50, v100, v48
	v_mul_f32_e32 v44, v50, v44
	v_mul_f32_e32 v50, v101, v48
	v_mul_f32_e32 v45, v50, v45
	v_mul_f32_e32 v50, v102, v48
	v_mul_f32_e32 v46, v50, v46
	v_mul_f32_e32 v50, v103, v48
	v_mul_f32_e32 v47, v50, v47
	v_mul_f32_e32 v50, v88, v48
	v_mul_f32_e32 v40, v50, v40
	v_mul_f32_e32 v50, v89, v48
	v_mul_f32_e32 v40, 0xbfb8aa3b, v40
	v_mul_f32_e32 v41, v50, v41
	v_exp_f32_e32 v40, v40
	v_mul_f32_e32 v41, 0xbfb8aa3b, v41
	v_exp_f32_e32 v41, v41
	v_mul_f32_e32 v44, 0xbfb8aa3b, v44
	v_add_f32_e32 v40, 1.0, v40
	v_rcp_f32_e32 v50, v40
	v_add_f32_e32 v40, 1.0, v41
	v_mul_f32_e32 v41, v90, v48
	v_mul_f32_e32 v41, v41, v42
	v_cvt_f32_i32_e32 v42, v43
	v_mul_f32_e32 v43, v91, v48
	v_mul_f32_e32 v45, 0xbfb8aa3b, v45
	v_mul_f32_e32 v41, 0xbfb8aa3b, v41
	v_mul_f32_e32 v42, v43, v42
	v_exp_f32_e32 v44, v44
	v_exp_f32_e32 v45, v45
	v_mul_f32_e32 v46, 0xbfb8aa3b, v46
	v_mul_f32_e32 v47, 0xbfb8aa3b, v47
	v_exp_f32_e32 v41, v41
	v_mul_f32_e32 v42, 0xbfb8aa3b, v42
	v_exp_f32_e32 v46, v46
	v_exp_f32_e32 v47, v47
	v_exp_f32_e32 v42, v42
	v_add_f32_e32 v44, 1.0, v44
	v_add_f32_e32 v45, 1.0, v45
	v_rcp_f32_e32 v43, v40
	v_add_f32_e32 v40, 1.0, v41
	v_rcp_f32_e32 v44, v44
	v_rcp_f32_e32 v45, v45
	v_add_f32_e32 v46, 1.0, v46
	v_add_f32_e32 v47, 1.0, v47
	v_rcp_f32_e32 v51, v40
	v_add_f32_e32 v40, 1.0, v42
	v_rcp_f32_e32 v46, v46
	v_rcp_f32_e32 v47, v47
	v_rcp_f32_e32 v52, v40
	v_cvt_pk_bf16_f32 v40, v44, v45
	v_mad_i64_i32 v[44:45], s[2:3], v49, s12, v[132:133]
	v_cvt_pk_bf16_f32 v41, v46, v47
	v_cvt_pk_bf16_f32 v42, v50, v43
	v_cvt_pk_bf16_f32 v43, v51, v52
	v_lshl_add_u64 v[44:45], v[44:45], 0, v[134:135]
	global_store_dwordx4 v[44:45], v[40:43], off
	s_nop 1
	v_mul_f32_e32 v40, v76, v48
	v_mul_f32_e32 v36, v40, v36
	v_mul_f32_e32 v40, v77, v48
	v_mul_f32_e32 v37, v40, v37
	v_mul_f32_e32 v40, v78, v48
	v_mul_f32_e32 v38, v40, v38
	v_mul_f32_e32 v40, v79, v48
	v_mul_f32_e32 v39, v40, v39
	v_mul_f32_e32 v40, v92, v48
	v_mul_f32_e32 v32, v40, v32
	v_mul_f32_e32 v40, v93, v48
	v_mul_f32_e32 v32, 0xbfb8aa3b, v32
	v_mul_f32_e32 v33, v40, v33
	v_exp_f32_e32 v32, v32
	v_mul_f32_e32 v33, 0xbfb8aa3b, v33
	v_exp_f32_e32 v33, v33
	v_mul_f32_e32 v36, 0xbfb8aa3b, v36
	v_add_f32_e32 v32, 1.0, v32
	v_rcp_f32_e32 v40, v32
	v_add_f32_e32 v32, 1.0, v33
	v_mul_f32_e32 v33, v94, v48
	v_mul_f32_e32 v33, v33, v34
	v_cvt_f32_i32_e32 v34, v35
	v_mul_f32_e32 v35, v95, v48
	v_mul_f32_e32 v33, 0xbfb8aa3b, v33
	v_mul_f32_e32 v37, 0xbfb8aa3b, v37
	v_mul_f32_e32 v34, v35, v34
	v_mul_f32_e32 v38, 0xbfb8aa3b, v38
	v_mul_f32_e32 v39, 0xbfb8aa3b, v39
	v_exp_f32_e32 v33, v33
	v_mul_f32_e32 v34, 0xbfb8aa3b, v34
	v_exp_f32_e32 v36, v36
	v_exp_f32_e32 v37, v37
	v_exp_f32_e32 v38, v38
	v_exp_f32_e32 v39, v39
	v_exp_f32_e32 v34, v34
	v_rcp_f32_e32 v35, v32
	v_add_f32_e32 v32, 1.0, v33
	v_add_f32_e32 v36, 1.0, v36
	v_add_f32_e32 v37, 1.0, v37
	v_add_f32_e32 v38, 1.0, v38
	v_add_f32_e32 v39, 1.0, v39
	v_rcp_f32_e32 v41, v32
	v_add_f32_e32 v32, 1.0, v34
	v_rcp_f32_e32 v36, v36
	v_rcp_f32_e32 v37, v37
	v_rcp_f32_e32 v38, v38
	v_rcp_f32_e32 v39, v39
	v_rcp_f32_e32 v42, v32
	v_cvt_pk_bf16_f32 v32, v36, v37
	v_cvt_pk_bf16_f32 v34, v40, v35
	v_cvt_pk_bf16_f32 v33, v38, v39
	v_cvt_pk_bf16_f32 v35, v41, v42
	global_store_dwordx4 v[44:45], v[32:35], off offset:256
	s_nop 1
	v_mov_b32_e32 v32, v215
	s_nop 0
	v_add_u32_e32 v33, 0xa0, v168
	v_mul_f32_e32 v34, v100, v32
	v_mul_f32_e32 v28, v34, v28
	v_mul_f32_e32 v34, v101, v32
	v_mul_f32_e32 v29, v34, v29
	v_mul_f32_e32 v34, v102, v32
	v_mul_f32_e32 v30, v34, v30
	v_mul_f32_e32 v34, v103, v32
	v_mul_f32_e32 v31, v34, v31
	v_mul_f32_e32 v34, v88, v32
	v_mul_f32_e32 v24, v34, v24
	v_mul_f32_e32 v34, v89, v32
	v_mul_f32_e32 v24, 0xbfb8aa3b, v24
	v_mul_f32_e32 v25, v34, v25
	v_exp_f32_e32 v24, v24
	v_mul_f32_e32 v25, 0xbfb8aa3b, v25
	v_exp_f32_e32 v25, v25
	v_mul_f32_e32 v28, 0xbfb8aa3b, v28
	v_add_f32_e32 v24, 1.0, v24
	v_rcp_f32_e32 v34, v24
	v_add_f32_e32 v24, 1.0, v25
	v_mul_f32_e32 v25, v90, v32
	v_mul_f32_e32 v25, v25, v26
	v_cvt_f32_i32_e32 v26, v27
	v_mul_f32_e32 v27, v91, v32
	v_mul_f32_e32 v29, 0xbfb8aa3b, v29
	v_mul_f32_e32 v25, 0xbfb8aa3b, v25
	v_mul_f32_e32 v26, v27, v26
	v_exp_f32_e32 v28, v28
	v_exp_f32_e32 v29, v29
	v_mul_f32_e32 v30, 0xbfb8aa3b, v30
	v_mul_f32_e32 v31, 0xbfb8aa3b, v31
	v_exp_f32_e32 v25, v25
	v_mul_f32_e32 v26, 0xbfb8aa3b, v26
	v_exp_f32_e32 v30, v30
	v_exp_f32_e32 v31, v31
	v_exp_f32_e32 v26, v26
	v_add_f32_e32 v28, 1.0, v28
	v_add_f32_e32 v29, 1.0, v29
	v_rcp_f32_e32 v27, v24
	v_add_f32_e32 v24, 1.0, v25
	v_rcp_f32_e32 v28, v28
	v_rcp_f32_e32 v29, v29
	v_add_f32_e32 v30, 1.0, v30
	v_add_f32_e32 v31, 1.0, v31
	v_rcp_f32_e32 v35, v24
	v_add_f32_e32 v24, 1.0, v26
	v_rcp_f32_e32 v30, v30
	v_rcp_f32_e32 v31, v31
	v_rcp_f32_e32 v36, v24
	v_cvt_pk_bf16_f32 v24, v28, v29
	v_mad_i64_i32 v[28:29], s[2:3], v33, s12, v[132:133]
	v_cvt_pk_bf16_f32 v25, v30, v31
	v_cvt_pk_bf16_f32 v26, v34, v27
	v_cvt_pk_bf16_f32 v27, v35, v36
	v_lshl_add_u64 v[28:29], v[28:29], 0, v[134:135]
	global_store_dwordx4 v[28:29], v[24:27], off
	s_nop 1
	v_mul_f32_e32 v24, v76, v32
	v_mul_f32_e32 v20, v24, v20
	v_mul_f32_e32 v24, v77, v32
	v_mul_f32_e32 v21, v24, v21
	v_mul_f32_e32 v24, v78, v32
	v_mul_f32_e32 v22, v24, v22
	v_mul_f32_e32 v24, v79, v32
	v_mul_f32_e32 v23, v24, v23
	v_mul_f32_e32 v24, v92, v32
	v_mul_f32_e32 v16, v24, v16
	v_mul_f32_e32 v24, v93, v32
	v_mul_f32_e32 v16, 0xbfb8aa3b, v16
	v_mul_f32_e32 v17, v24, v17
	v_exp_f32_e32 v16, v16
	v_mul_f32_e32 v17, 0xbfb8aa3b, v17
	v_exp_f32_e32 v17, v17
	v_mul_f32_e32 v20, 0xbfb8aa3b, v20
	v_add_f32_e32 v16, 1.0, v16
	v_rcp_f32_e32 v24, v16
	v_add_f32_e32 v16, 1.0, v17
	v_mul_f32_e32 v17, v94, v32
	v_mul_f32_e32 v17, v17, v18
	v_cvt_f32_i32_e32 v18, v19
	v_mul_f32_e32 v19, v95, v32
	v_mul_f32_e32 v17, 0xbfb8aa3b, v17
	v_mul_f32_e32 v21, 0xbfb8aa3b, v21
	v_mul_f32_e32 v18, v19, v18
	v_mul_f32_e32 v22, 0xbfb8aa3b, v22
	v_mul_f32_e32 v23, 0xbfb8aa3b, v23
	v_exp_f32_e32 v17, v17
	v_mul_f32_e32 v18, 0xbfb8aa3b, v18
	v_exp_f32_e32 v20, v20
	v_exp_f32_e32 v21, v21
	v_exp_f32_e32 v22, v22
	v_exp_f32_e32 v23, v23
	v_exp_f32_e32 v18, v18
	v_rcp_f32_e32 v19, v16
	v_add_f32_e32 v16, 1.0, v17
	v_add_f32_e32 v20, 1.0, v20
	v_add_f32_e32 v21, 1.0, v21
	v_add_f32_e32 v22, 1.0, v22
	v_add_f32_e32 v23, 1.0, v23
	v_rcp_f32_e32 v25, v16
	v_add_f32_e32 v16, 1.0, v18
	v_rcp_f32_e32 v20, v20
	v_rcp_f32_e32 v21, v21
	v_rcp_f32_e32 v22, v22
	v_rcp_f32_e32 v23, v23
	v_rcp_f32_e32 v26, v16
	v_cvt_pk_bf16_f32 v16, v20, v21
	v_cvt_pk_bf16_f32 v18, v24, v19
	v_cvt_pk_bf16_f32 v17, v22, v23
	v_cvt_pk_bf16_f32 v19, v25, v26
	global_store_dwordx4 v[28:29], v[16:19], off offset:256
	s_nop 1
	v_mov_b32_e32 v16, v216
	s_nop 0
	v_add_u32_e32 v17, 0xb0, v168
	v_mul_f32_e32 v18, v100, v16
	v_mul_f32_e32 v12, v18, v12
	v_mul_f32_e32 v18, v101, v16
	v_mul_f32_e32 v13, v18, v13
	v_mul_f32_e32 v18, v102, v16
	v_mul_f32_e32 v14, v18, v14
	v_mul_f32_e32 v18, v103, v16
	v_mul_f32_e32 v15, v18, v15
	v_mul_f32_e32 v18, v88, v16
	v_mul_f32_e32 v8, v18, v8
	v_mul_f32_e32 v18, v89, v16
	v_mul_f32_e32 v8, 0xbfb8aa3b, v8
	v_mul_f32_e32 v9, v18, v9
	v_exp_f32_e32 v8, v8
	v_mul_f32_e32 v9, 0xbfb8aa3b, v9
	v_exp_f32_e32 v9, v9
	v_mul_f32_e32 v12, 0xbfb8aa3b, v12
	v_add_f32_e32 v8, 1.0, v8
	v_rcp_f32_e32 v18, v8
	v_add_f32_e32 v8, 1.0, v9
	v_mul_f32_e32 v9, v90, v16
	v_mul_f32_e32 v9, v9, v10
	v_cvt_f32_i32_e32 v10, v11
	v_mul_f32_e32 v11, v91, v16
	v_mul_f32_e32 v13, 0xbfb8aa3b, v13
	v_mul_f32_e32 v9, 0xbfb8aa3b, v9
	v_mul_f32_e32 v10, v11, v10
	v_exp_f32_e32 v12, v12
	v_exp_f32_e32 v13, v13
	v_mul_f32_e32 v14, 0xbfb8aa3b, v14
	v_mul_f32_e32 v15, 0xbfb8aa3b, v15
	v_exp_f32_e32 v9, v9
	v_mul_f32_e32 v10, 0xbfb8aa3b, v10
	v_exp_f32_e32 v14, v14
	v_exp_f32_e32 v15, v15
	v_exp_f32_e32 v10, v10
	v_add_f32_e32 v12, 1.0, v12
	v_add_f32_e32 v13, 1.0, v13
	v_rcp_f32_e32 v11, v8
	v_add_f32_e32 v8, 1.0, v9
	v_rcp_f32_e32 v12, v12
	v_rcp_f32_e32 v13, v13
	v_add_f32_e32 v14, 1.0, v14
	v_add_f32_e32 v15, 1.0, v15
	v_rcp_f32_e32 v19, v8
	v_add_f32_e32 v8, 1.0, v10
	v_rcp_f32_e32 v14, v14
	v_rcp_f32_e32 v15, v15
	v_rcp_f32_e32 v20, v8
	v_cvt_pk_bf16_f32 v8, v12, v13
	v_mad_i64_i32 v[12:13], s[2:3], v17, s12, v[132:133]
	v_cvt_pk_bf16_f32 v9, v14, v15
	v_cvt_pk_bf16_f32 v10, v18, v11
	v_cvt_pk_bf16_f32 v11, v19, v20
	v_lshl_add_u64 v[12:13], v[12:13], 0, v[134:135]
	global_store_dwordx4 v[12:13], v[8:11], off
	s_nop 1
	v_mul_f32_e32 v8, v76, v16
	v_mul_f32_e32 v4, v8, v4
	v_mul_f32_e32 v8, v77, v16
	v_mul_f32_e32 v5, v8, v5
	v_mul_f32_e32 v8, v78, v16
	v_mul_f32_e32 v6, v8, v6
	v_mul_f32_e32 v8, v79, v16
	v_mul_f32_e32 v7, v8, v7
	v_mul_f32_e32 v8, v92, v16
	v_mul_f32_e32 v0, v8, v0
	v_mul_f32_e32 v8, v93, v16
	v_mul_f32_e32 v0, 0xbfb8aa3b, v0
	v_mul_f32_e32 v1, v8, v1
	v_exp_f32_e32 v0, v0
	v_mul_f32_e32 v1, 0xbfb8aa3b, v1
	v_exp_f32_e32 v1, v1
	v_mul_f32_e32 v4, 0xbfb8aa3b, v4
	v_add_f32_e32 v0, 1.0, v0
	v_rcp_f32_e32 v8, v0
	v_add_f32_e32 v0, 1.0, v1
	v_mul_f32_e32 v1, v94, v16
	v_mul_f32_e32 v1, v1, v2
	v_cvt_f32_i32_e32 v2, v3
	v_mul_f32_e32 v3, v95, v16
	v_mul_f32_e32 v1, 0xbfb8aa3b, v1
	v_mul_f32_e32 v5, 0xbfb8aa3b, v5
	v_mul_f32_e32 v2, v3, v2
	v_mul_f32_e32 v6, 0xbfb8aa3b, v6
	v_mul_f32_e32 v7, 0xbfb8aa3b, v7
	v_exp_f32_e32 v1, v1
	v_mul_f32_e32 v2, 0xbfb8aa3b, v2
	v_exp_f32_e32 v4, v4
	v_exp_f32_e32 v5, v5
	v_exp_f32_e32 v6, v6
	v_exp_f32_e32 v7, v7
	v_exp_f32_e32 v2, v2
	v_rcp_f32_e32 v3, v0
	v_add_f32_e32 v0, 1.0, v1
	v_add_f32_e32 v4, 1.0, v4
	v_add_f32_e32 v5, 1.0, v5
	v_add_f32_e32 v6, 1.0, v6
	v_add_f32_e32 v7, 1.0, v7
	v_rcp_f32_e32 v9, v0
	v_add_f32_e32 v0, 1.0, v2
	v_rcp_f32_e32 v4, v4
	v_rcp_f32_e32 v5, v5
	v_rcp_f32_e32 v6, v6
	v_rcp_f32_e32 v7, v7
	v_rcp_f32_e32 v10, v0
	v_cvt_pk_bf16_f32 v0, v4, v5
	v_cvt_pk_bf16_f32 v2, v8, v3
	v_cvt_pk_bf16_f32 v1, v6, v7
	v_cvt_pk_bf16_f32 v3, v9, v10
	global_store_dwordx4 v[12:13], v[0:3], off offset:256
	s_cbranch_vccnz .LBB0_1031
	s_andn2_b64 vcc, exec, s[6:7]
	s_cbranch_vccnz .LBB0_1030
	s_barrier
	s_branch .LBB0_1030

.LBB0_1394:
.LBB0_1395:
	s_mov_b64 s[20:21], 0xb000
	s_mul_hi_i32 s0, s76, 0x2e8ba2e9
	s_lshr_b32 s1, s0, 31
	s_ashr_i32 s0, s0, 5
	s_add_i32 s0, s0, s1
	s_mul_i32 s1, s0, 0xb0
	s_sub_i32 s14, s76, s1
	s_lshl_b32 s15, s0, 6
	s_lshl_b32 s4, s14, 5
	s_ashr_i32 s5, s4, 31
	s_waitcnt lgkmcnt(0)
	v_or_b32_e32 v6, s15, v42
	v_mov_b32_e32 v7, 0x5800
	v_mul_lo_u32 v6, v6, v7
	s_lshl_b32 s6, s4, 2
	v_add_u32_e32 v6, s6, v6
	v_mov_b32_e32 v7, 0
	v_lshl_add_u64 v[8:9], v[0:1], 0, v[6:7]
	v_lshl_add_u64 v[10:11], v[4:5], 0, v[6:7]
	global_load_dword v60, v[8:9], off
	v_lshl_add_u64 v[8:9], v[8:9], 0, s[20:21]
	global_load_dword v61, v[8:9], off
	v_lshl_add_u64 v[8:9], v[8:9], 0, s[20:21]
	global_load_dword v62, v[8:9], off
	v_lshl_add_u64 v[8:9], v[8:9], 0, s[20:21]
	global_load_dword v63, v[8:9], off
	v_lshl_add_u64 v[8:9], v[8:9], 0, s[20:21]
	global_load_dword v64, v[8:9], off
	v_lshl_add_u64 v[8:9], v[8:9], 0, s[20:21]
	global_load_dword v65, v[8:9], off
	v_lshl_add_u64 v[8:9], v[8:9], 0, s[20:21]
	global_load_dword v66, v[8:9], off
	v_lshl_add_u64 v[8:9], v[8:9], 0, s[20:21]
	global_load_dword v67, v[8:9], off
	v_lshl_add_u64 v[8:9], v[8:9], 0, s[20:21]
	global_load_dword v68, v[8:9], off
	v_lshl_add_u64 v[8:9], v[8:9], 0, s[20:21]
	global_load_dword v69, v[8:9], off
	v_lshl_add_u64 v[8:9], v[8:9], 0, s[20:21]
	global_load_dword v70, v[8:9], off
	v_lshl_add_u64 v[8:9], v[8:9], 0, s[20:21]
	global_load_dword v71, v[8:9], off
	v_lshl_add_u64 v[8:9], v[8:9], 0, s[20:21]
	global_load_dword v72, v[8:9], off
	v_lshl_add_u64 v[8:9], v[8:9], 0, s[20:21]
	global_load_dword v73, v[8:9], off
	v_lshl_add_u64 v[8:9], v[8:9], 0, s[20:21]
	global_load_dword v74, v[8:9], off
	v_lshl_add_u64 v[8:9], v[8:9], 0, s[20:21]
	global_load_dword v75, v[8:9], off
	v_lshl_add_u64 v[8:9], v[8:9], 0, s[20:21]
	global_load_dword v76, v[8:9], off
	v_lshl_add_u64 v[8:9], v[8:9], 0, s[20:21]
	global_load_dword v77, v[8:9], off
	v_lshl_add_u64 v[8:9], v[8:9], 0, s[20:21]
	global_load_dword v78, v[8:9], off
	v_lshl_add_u64 v[8:9], v[8:9], 0, s[20:21]
	global_load_dword v79, v[8:9], off
	v_lshl_add_u64 v[8:9], v[8:9], 0, s[20:21]
	global_load_dword v80, v[8:9], off
	v_lshl_add_u64 v[8:9], v[8:9], 0, s[20:21]
	global_load_dword v81, v[8:9], off
	v_lshl_add_u64 v[8:9], v[8:9], 0, s[20:21]
	global_load_dword v82, v[8:9], off
	v_lshl_add_u64 v[8:9], v[8:9], 0, s[20:21]
	global_load_dword v83, v[8:9], off
	v_lshl_add_u64 v[8:9], v[8:9], 0, s[20:21]
	global_load_dword v84, v[8:9], off
	v_lshl_add_u64 v[8:9], v[8:9], 0, s[20:21]
	global_load_dword v85, v[8:9], off
	v_lshl_add_u64 v[8:9], v[8:9], 0, s[20:21]
	global_load_dword v86, v[8:9], off
	v_lshl_add_u64 v[8:9], v[8:9], 0, s[20:21]
	global_load_dword v87, v[8:9], off
	v_lshl_add_u64 v[8:9], v[8:9], 0, s[20:21]
	global_load_dword v88, v[8:9], off
	v_lshl_add_u64 v[8:9], v[8:9], 0, s[20:21]
	global_load_dword v89, v[8:9], off
	v_lshl_add_u64 v[8:9], v[8:9], 0, s[20:21]
	global_load_dword v90, v[8:9], off
	v_lshl_add_u64 v[8:9], v[8:9], 0, s[20:21]
	global_load_dword v91, v[8:9], off
	global_load_dword v92, v[10:11], off
	v_lshl_add_u64 v[10:11], v[10:11], 0, s[20:21]
	global_load_dword v93, v[10:11], off
	v_lshl_add_u64 v[10:11], v[10:11], 0, s[20:21]
	global_load_dword v94, v[10:11], off
	v_lshl_add_u64 v[10:11], v[10:11], 0, s[20:21]
	global_load_dword v95, v[10:11], off
	v_lshl_add_u64 v[10:11], v[10:11], 0, s[20:21]
	global_load_dword v96, v[10:11], off
	v_lshl_add_u64 v[10:11], v[10:11], 0, s[20:21]
	global_load_dword v97, v[10:11], off
	v_lshl_add_u64 v[10:11], v[10:11], 0, s[20:21]
	global_load_dword v98, v[10:11], off
	v_lshl_add_u64 v[10:11], v[10:11], 0, s[20:21]
	global_load_dword v99, v[10:11], off
	v_lshl_add_u64 v[10:11], v[10:11], 0, s[20:21]
	global_load_dword v100, v[10:11], off
	v_lshl_add_u64 v[10:11], v[10:11], 0, s[20:21]
	global_load_dword v101, v[10:11], off
	v_lshl_add_u64 v[10:11], v[10:11], 0, s[20:21]
	global_load_dword v102, v[10:11], off
	v_lshl_add_u64 v[10:11], v[10:11], 0, s[20:21]
	global_load_dword v103, v[10:11], off
	v_lshl_add_u64 v[10:11], v[10:11], 0, s[20:21]
	global_load_dword v104, v[10:11], off
	v_lshl_add_u64 v[10:11], v[10:11], 0, s[20:21]
	global_load_dword v105, v[10:11], off
	v_lshl_add_u64 v[10:11], v[10:11], 0, s[20:21]
	global_load_dword v106, v[10:11], off
	v_lshl_add_u64 v[10:11], v[10:11], 0, s[20:21]
	global_load_dword v107, v[10:11], off
	v_lshl_add_u64 v[10:11], v[10:11], 0, s[20:21]
	global_load_dword v108, v[10:11], off
	v_lshl_add_u64 v[10:11], v[10:11], 0, s[20:21]
	global_load_dword v109, v[10:11], off
	v_lshl_add_u64 v[10:11], v[10:11], 0, s[20:21]
	global_load_dword v110, v[10:11], off
	v_lshl_add_u64 v[10:11], v[10:11], 0, s[20:21]
	global_load_dword v111, v[10:11], off
	v_lshl_add_u64 v[10:11], v[10:11], 0, s[20:21]
	global_load_dword v112, v[10:11], off
	v_lshl_add_u64 v[10:11], v[10:11], 0, s[20:21]
	global_load_dword v113, v[10:11], off
	v_lshl_add_u64 v[10:11], v[10:11], 0, s[20:21]
	global_load_dword v114, v[10:11], off
	v_lshl_add_u64 v[10:11], v[10:11], 0, s[20:21]
	global_load_dword v115, v[10:11], off
	v_lshl_add_u64 v[10:11], v[10:11], 0, s[20:21]
	global_load_dword v116, v[10:11], off
	v_lshl_add_u64 v[10:11], v[10:11], 0, s[20:21]
	global_load_dword v117, v[10:11], off
	v_lshl_add_u64 v[10:11], v[10:11], 0, s[20:21]
	global_load_dword v118, v[10:11], off
	v_lshl_add_u64 v[10:11], v[10:11], 0, s[20:21]
	global_load_dword v119, v[10:11], off
	v_lshl_add_u64 v[10:11], v[10:11], 0, s[20:21]
	global_load_dword v120, v[10:11], off
	v_lshl_add_u64 v[10:11], v[10:11], 0, s[20:21]
	global_load_dword v121, v[10:11], off
	v_lshl_add_u64 v[10:11], v[10:11], 0, s[20:21]
	global_load_dword v122, v[10:11], off
	v_lshl_add_u64 v[10:11], v[10:11], 0, s[20:21]
	global_load_dword v123, v[10:11], off
	s_waitcnt vmcnt(32)
	v_max3_f32 v12, |v60|, |v61|, |v62|
	v_max3_f32 v12, v12, |v63|, |v64|
	v_max3_f32 v12, v12, |v65|, |v66|
	v_max3_f32 v12, v12, |v67|, |v68|
	v_max3_f32 v12, v12, |v69|, |v70|
	v_max3_f32 v12, v12, |v71|, |v72|
	v_max3_f32 v12, v12, |v73|, |v74|
	v_max3_f32 v12, v12, |v75|, |v76|
	v_max3_f32 v12, v12, |v77|, |v78|
	v_max3_f32 v12, v12, |v79|, |v80|
	v_max3_f32 v12, v12, |v81|, |v82|
	v_max3_f32 v12, v12, |v83|, |v84|
	v_max3_f32 v12, v12, |v85|, |v86|
	v_max3_f32 v12, v12, |v87|, |v88|
	v_max3_f32 v12, v12, |v89|, |v90|
	v_max_f32_e64 v12, v12, |v91|
	s_waitcnt vmcnt(0)
	v_max3_f32 v13, |v92|, |v93|, |v94|
	v_max3_f32 v13, v13, |v95|, |v96|
	v_max3_f32 v13, v13, |v97|, |v98|
	v_max3_f32 v13, v13, |v99|, |v100|
	v_max3_f32 v13, v13, |v101|, |v102|
	v_max3_f32 v13, v13, |v103|, |v104|
	v_max3_f32 v13, v13, |v105|, |v106|
	v_max3_f32 v13, v13, |v107|, |v108|
	v_max3_f32 v13, v13, |v109|, |v110|
	v_max3_f32 v13, v13, |v111|, |v112|
	v_max3_f32 v13, v13, |v113|, |v114|
	v_max3_f32 v13, v13, |v115|, |v116|
	v_max3_f32 v13, v13, |v117|, |v118|
	v_max3_f32 v13, v13, |v119|, |v120|
	v_max3_f32 v13, v13, |v121|, |v122|
	v_max_f32_e64 v13, v13, |v123|
	ds_bpermute_b32 v14, v43, v12
	ds_bpermute_b32 v15, v43, v13
	s_lshl_b32 s2, s14, 6
	s_and_b32 s2, s2, 0xffffff00
	s_and_b32 s3, s4, 0x60
	s_or_b32 s2, s2, s3
	s_ashr_i32 s3, s2, 31
	v_lshl_add_u64 v[16:17], s[2:3], 2, v[2:3]
	s_waitcnt lgkmcnt(0)
	v_max_f32_e32 v12, v12, v14
	v_max_f32_e32 v13, v13, v15
	s_and_saveexec_b64 s[0:1], vcc
	global_atomic_umax v[16:17], v12, off
	global_atomic_umax v[16:17], v13, off offset:512
	s_or_b64 exec, exec, s[0:1]
	v_readlane_b32 s0, v252, 5
	s_nop 3
	s_add_i32 s76, s76, s0
	s_cmpk_gt_i32 s76, 0x15ff
	v_readlane_b32 s1, v252, 6
	s_cbranch_scc0 .LBB0_1395

.LBB0_1557:
	s_ashr_i32 s2, s0, 9
	s_ashr_i32 s3, s2, 31
	s_lshl_b32 s1, s0, 6
	s_lshl_b64 s[2:3], s[2:3], 12
	s_and_b32 s1, s1, 0xfc0
	s_or_b32 s2, s2, s1
	s_ashr_i32 s1, s0, 31
	s_lshl_b64 s[4:5], s[0:1], 15
	s_lshl_b32 s1, s0, 1
	v_mov_b32_e32 v21, v190
	s_and_b32 s1, s1, 0x380
	s_lshl_b32 s6, s1, 2
	v_readlane_b32 s8, v251, 18
	v_ashrrev_i32_e32 v8, 5, v21
	v_readlane_b32 s9, v251, 19
	s_add_u32 s6, s8, s6
	v_lshlrev_b32_e32 v0, 4, v21
	v_ashrrev_i32_e32 v9, 31, v8
	s_addc_u32 s7, s9, 0
	v_and_b32_e32 v148, 0x1f0, v0
	v_lshl_add_u64 v[0:1], s[2:3], 0, v[8:9]
	v_lshl_add_u64 v[4:5], s[6:7], 0, v[148:149]
	v_lshlrev_b64 v[0:1], 12, v[0:1]
	v_lshl_add_u64 v[0:1], v[4:5], 0, v[0:1]
	global_load_dwordx4 v[60:63], v[0:1], off
	v_add_u32_e32 v6, 0, v148
	s_movk_i32 s8, 0x210
	v_mad_u64_u32 v[8:9], s[6:7], v8, s8, v[6:7]
	v_add_u32_e32 v20, 0x200, v21
	v_add_u32_e32 v23, 0x400, v21
	v_add_u32_e32 v32, 0x600, v21
	v_ashrrev_i32_e32 v18, 4, v21
	v_ashrrev_i32_e32 v19, 31, v18
	v_ashrrev_i32_e32 v16, 4, v20
	v_ashrrev_i32_e32 v17, 31, v16
	v_mov_b32_e32 v76, v8
	v_ashrrev_i32_e32 v8, 5, v20
	v_ashrrev_i32_e32 v9, 31, v8
	v_lshl_add_u64 v[0:1], s[2:3], 0, v[8:9]
	v_lshlrev_b64 v[0:1], 12, v[0:1]
	v_lshl_add_u64 v[0:1], v[4:5], 0, v[0:1]
	global_load_dwordx4 v[64:67], v[0:1], off
	v_ashrrev_i32_e32 v8, 5, v23
	v_ashrrev_i32_e32 v9, 31, v8
	v_lshl_add_u64 v[0:1], s[2:3], 0, v[8:9]
	v_lshlrev_b64 v[0:1], 12, v[0:1]
	v_lshl_add_u64 v[0:1], v[4:5], 0, v[0:1]
	global_load_dwordx4 v[68:71], v[0:1], off
	v_ashrrev_i32_e32 v8, 5, v32
	v_ashrrev_i32_e32 v9, 31, v8
	v_lshl_add_u64 v[0:1], s[2:3], 0, v[8:9]
	v_lshlrev_b64 v[0:1], 12, v[0:1]
	v_lshl_add_u64 v[0:1], v[4:5], 0, v[0:1]
	global_load_dwordx4 v[72:75], v[0:1], off
	v_readlane_b32 s6, v251, 2
	v_readlane_b32 s7, v251, 3
	s_mov_b32 s9, s7
	s_lshl_b32 s8, s1, 1
	v_writelane_b32 v251, s6, 2
	s_add_u32 s4, s34, s4
	v_lshlrev_b32_e32 v0, 3, v21
	v_and_b32_e32 v3, 63, v21
	v_and_b32_e32 v22, 0x78, v0
	v_or_b32_e32 v0, s2, v3
	v_mov_b32_e32 v1, s3
	v_lshlrev_b64 v[0:1], 11, v[0:1]
	v_lshl_add_u64 v[0:1], s[24:25], 0, v[0:1]
	v_or_b32_e32 v2, s1, v22
	v_writelane_b32 v251, s7, 3
	v_lshl_add_u64 v[24:25], v[0:1], 0, s[8:9]
	v_lshl_add_u64 v[0:1], s[2:3], 0, v[18:19]
	v_lshlrev_b64 v[0:1], 11, v[0:1]
	v_lshlrev_b32_e32 v6, 1, v2
	v_readlane_b32 s6, v251, 43
	v_or_b32_e32 v0, v0, v6
	v_readlane_b32 s7, v251, 44
	v_lshlrev_b32_e32 v28, 1, v3
	v_lshl_add_u64 v[2:3], s[26:27], 0, v[0:1]
	v_lshl_add_u64 v[0:1], s[6:7], 0, v[0:1]
	global_load_dwordx4 v[8:11], v[2:3], off
	global_load_dwordx4 v[12:15], v[0:1], off
	v_ashrrev_i32_e32 v0, 3, v21
	v_and_b32_e32 v0, -8, v0
	v_ashrrev_i32_e32 v1, 31, v0
	v_lshl_add_u64 v[2:3], v[0:1], 1, v[24:25]
	s_movk_i32 s8, 0x90
	v_mul_lo_u32 v4, v0, s8
	global_load_dwordx4 v[80:83], v[2:3], off
	v_add_u32_e32 v29, s80, v28
	v_add_u32_e32 v5, v29, v4
	v_add3_u32 v4, s80, v4, v28
	v_lshlrev_b32_e32 v148, 1, v22
	s_movk_i32 s9, 0x90
	v_mov_b32_e32 v77, v5
	v_mov_b32_e32 v78, v4
	v_lshl_add_u64 v[0:1], s[2:3], 0, v[16:17]
	v_ashrrev_i32_e32 v17, 3, v20
	v_and_b32_e32 v26, -8, v17
	v_ashrrev_i32_e32 v27, 31, v26
	v_lshl_add_u64 v[24:25], v[26:27], 1, v[24:25]
	v_mul_lo_u32 v17, v26, s8
	global_load_dwordx4 v[84:87], v[24:25], off
	v_lshlrev_b64 v[4:5], 11, v[0:1]
	v_or_b32_e32 v4, v4, v6
	v_lshl_add_u64 v[0:1], s[26:27], 0, v[4:5]
	v_lshl_add_u64 v[4:5], s[6:7], 0, v[4:5]
	v_add_u32_e32 v19, v29, v17
	v_add3_u32 v17, s80, v17, v28
	v_readlane_b32 s6, v253, 53
	global_load_dwordx4 v[0:3], v[0:1], off
	s_addc_u32 s5, s6, s5
	global_load_dwordx4 v[4:7], v[4:5], off
	v_lshl_add_u64 v[28:29], s[4:5], 0, v[148:149]
	s_add_i32 s8, 0, 0x1a000
	v_add_u32_e32 v20, s8, v148
	s_movk_i32 s6, 0x110
	v_mad_u64_u32 v[30:31], s[4:5], v18, s6, v[20:21]
	v_mov_b32_e32 v79, v19
	v_mov_b32_e32 v88, v17
	v_mov_b32_e32 v89, v30
	v_lshlrev_b32_e32 v24, 7, v18
	v_ashrrev_i32_e32 v25, 31, v24
	v_lshl_add_u64 v[24:25], v[24:25], 1, v[28:29]
	global_load_dwordx4 v[92:95], v[24:25], off
	v_ashrrev_i32_e32 v17, 4, v23
	v_lshlrev_b32_e32 v24, 7, v16
	v_ashrrev_i32_e32 v25, 31, v24
	v_lshl_add_u64 v[24:25], v[24:25], 1, v[28:29]
	global_load_dwordx4 v[96:99], v[24:25], off
	v_lshlrev_b32_e32 v24, 7, v17
	v_ashrrev_i32_e32 v25, 31, v24
	v_lshl_add_u64 v[24:25], v[24:25], 1, v[28:29]
	global_load_dwordx4 v[100:103], v[24:25], off
	v_ashrrev_i32_e32 v17, 4, v32
	v_lshlrev_b32_e32 v24, 7, v17
	v_ashrrev_i32_e32 v25, 31, v24
	v_lshl_add_u64 v[24:25], v[24:25], 1, v[28:29]
	global_load_dwordx4 v[104:107], v[24:25], off
	s_movk_i32 s4, 0x2100
	s_waitcnt vmcnt(13)
	ds_write_b128 v76, v[60:63]
	s_waitcnt vmcnt(12)
	ds_write_b128 v76, v[64:67] offset:8448
	s_waitcnt vmcnt(11)
	ds_write_b128 v76, v[68:71] offset:16896
	s_waitcnt vmcnt(10)
	ds_write_b128 v76, v[72:75] offset:25344
	s_waitcnt vmcnt(7)
	ds_write_b16 v77, v80
	ds_write_b16_d16_hi v78, v80 offset:144
	ds_write_b16 v77, v81 offset:288
	ds_write_b16_d16_hi v78, v81 offset:432
	ds_write_b16 v77, v82 offset:576
	ds_write_b16_d16_hi v78, v82 offset:720
	ds_write_b16 v77, v83 offset:864
	ds_write_b16_d16_hi v78, v83 offset:1008
	s_waitcnt vmcnt(6)
	ds_write_b16 v79, v84
	ds_write_b16_d16_hi v88, v84 offset:144
	ds_write_b16 v79, v85 offset:288
	ds_write_b16_d16_hi v88, v85 offset:432
	ds_write_b16 v79, v86 offset:576
	ds_write_b16_d16_hi v88, v86 offset:720
	ds_write_b16 v79, v87 offset:864
	ds_write_b16_d16_hi v88, v87 offset:1008
	s_waitcnt vmcnt(3)
	ds_write_b128 v89, v[92:95]
	s_waitcnt vmcnt(2)
	ds_write_b128 v89, v[96:99] offset:8704
	s_waitcnt vmcnt(1)
	ds_write_b128 v89, v[100:103] offset:17408
	s_waitcnt vmcnt(0)
	ds_write_b128 v89, v[104:107] offset:26112
	v_and_b32_e32 v28, 0x7f, v21
	v_ashrrev_i32_e32 v27, 7, v21
	v_lshl_add_u32 v17, v28, 2, 0
	v_mul_lo_u32 v19, v27, s4
	v_add_u32_e32 v25, v17, v19
	s_waitcnt lgkmcnt(0)
	s_barrier
	ds_read2_b32 v[30:31], v25 offset1:132
	v_add_u32_e32 v26, 0x400, v25
	v_add_u32_e32 v29, 0x800, v25
	v_add_u32_e32 v23, 0xc00, v25
	v_add_u32_e32 v24, 0x1000, v25
	s_waitcnt lgkmcnt(0)
	v_add_f32_e32 v17, 0, v30
	v_add_f32_e32 v19, v17, v31
	ds_read2_b32 v[30:31], v26 offset0:8 offset1:140
	ds_write2_b32 v25, v17, v19 offset1:132
	v_cmp_lt_i32_e32 vcc, 0, v27
	s_waitcnt lgkmcnt(1)
	v_add_f32_e32 v17, v19, v30
	v_add_f32_e32 v19, v17, v31
	ds_read2_b32 v[30:31], v29 offset0:16 offset1:148
	ds_write2_b32 v26, v17, v19 offset0:8 offset1:140
	s_waitcnt lgkmcnt(1)
	v_add_f32_e32 v17, v19, v30
	v_add_f32_e32 v19, v17, v31
	ds_read2_b32 v[30:31], v23 offset0:24 offset1:156
	ds_write2_b32 v29, v17, v19 offset0:16 offset1:148
	s_waitcnt lgkmcnt(1)
	v_add_f32_e32 v17, v19, v30
	v_add_f32_e32 v19, v17, v31
	ds_read2_b32 v[30:31], v24 offset0:32 offset1:164
	ds_write2_b32 v23, v17, v19 offset0:24 offset1:156
	s_waitcnt lgkmcnt(1)
	v_add_f32_e32 v17, v19, v30
	v_add_u32_e32 v19, 0x1400, v25
	v_add_f32_e32 v20, v17, v31
	ds_read2_b32 v[30:31], v19 offset0:40 offset1:172
	ds_write2_b32 v24, v17, v20 offset0:32 offset1:164
	s_waitcnt lgkmcnt(1)
	v_add_f32_e32 v17, v20, v30
	v_add_u32_e32 v20, 0x1800, v25
	v_add_f32_e32 v32, v17, v31
	ds_read2_b32 v[30:31], v20 offset0:48 offset1:180
	ds_write2_b32 v19, v17, v32 offset0:40 offset1:172
	s_waitcnt lgkmcnt(1)
	v_add_f32_e32 v17, v32, v30
	v_add_f32_e32 v32, v17, v31
	ds_write2_b32 v20, v17, v32 offset0:48 offset1:180
	v_add_u32_e32 v17, 0x1c00, v25
	ds_read2_b32 v[30:31], v17 offset0:56 offset1:188
	s_waitcnt lgkmcnt(0)
	v_add_f32_e32 v30, v32, v30
	v_add_f32_e32 v31, v30, v31
	ds_write2_b32 v17, v30, v31 offset0:56 offset1:188
	v_lshl_add_u32 v30, v21, 2, 0
	ds_write_b32 v30, v31 offset:33792
	s_waitcnt lgkmcnt(0)
	s_barrier
	s_and_saveexec_b64 s[4:5], vcc
	s_cbranch_execz .LBB0_1561
	v_readlane_b32 s6, v254, 54
	s_nop 1
	v_lshl_add_u32 v30, v28, 2, s6
	v_mov_b32_e32 v28, 0
	s_mov_b64 s[6:7], 0

.LBB0_1970:
	v_lshl_or_b32 v48, s23, 8, v176
	v_readlane_b32 s24, v254, 0
	v_lshl_add_u32 v166, s22, 8, v174
	v_readlane_b32 s44, v251, 8
	v_ashrrev_i32_e32 v49, 31, v48
	v_readlane_b32 s25, v254, 1
	v_ashrrev_i32_e32 v167, 31, v166
	v_readlane_b32 s50, v251, 14
	v_readlane_b32 s51, v251, 15
	v_lshl_add_u64 v[56:57], v[48:49], 2, s[24:25]
	global_load_dwordx4 v[52:55], v[56:57], off offset:16
	global_load_dwordx4 v[60:63], v[56:57], off
	global_load_dwordx4 v[48:51], v[56:57], off offset:528
	s_nop 0
	global_load_dwordx4 v[56:59], v[56:57], off offset:512
	v_lshl_add_u64 v[168:169], v[166:167], 2, s[50:51]
	global_load_dword v170, v[168:169], off
	global_load_dword v200, v[168:169], off offset:64
	global_load_dword v201, v[168:169], off offset:128
	global_load_dword v202, v[168:169], off offset:192
	global_load_dword v203, v[168:169], off offset:512
	global_load_dword v204, v[168:169], off offset:576
	global_load_dword v205, v[168:169], off offset:640
	global_load_dword v206, v[168:169], off offset:704
	v_cvt_f32_i32_e32 v141, v141
	v_cvt_f32_i32_e32 v140, v140
	v_cvt_f32_i32_e32 v137, v137
	v_cvt_f32_i32_e32 v136, v136
	v_cvt_f32_i32_e32 v139, v139
	v_cvt_f32_i32_e32 v138, v138
	v_cvt_f32_i32_e32 v133, v133
	v_cvt_f32_i32_e32 v132, v132
	v_cvt_f32_i32_e32 v129, v129
	v_cvt_f32_i32_e32 v128, v128
	v_cvt_f32_i32_e32 v131, v131
	v_cvt_f32_i32_e32 v130, v130
	v_readlane_b32 s24, v251, 39
	s_lshl_b32 s22, s23, 7
	v_readlane_b32 s25, v251, 40
	s_ashr_i32 s23, s22, 31
	s_lshl_b64 s[22:23], s[22:23], 1
	v_cvt_f32_i32_e32 v125, v125
	v_cvt_f32_i32_e32 v124, v124
	v_cvt_f32_i32_e32 v121, v121
	v_cvt_f32_i32_e32 v120, v120
	v_cvt_f32_i32_e32 v123, v123
	v_cvt_f32_i32_e32 v122, v122
	v_cvt_f32_i32_e32 v117, v117
	v_cvt_f32_i32_e32 v116, v116
	v_cvt_f32_i32_e32 v113, v113
	v_cvt_f32_i32_e32 v112, v112
	v_cvt_f32_i32_e32 v115, v115
	v_cvt_f32_i32_e32 v114, v114
	v_cvt_f32_i32_e32 v109, v109
	v_cvt_f32_i32_e32 v108, v108
	v_cvt_f32_i32_e32 v105, v105
	v_cvt_f32_i32_e32 v104, v104
	v_cvt_f32_i32_e32 v107, v107
	v_cvt_f32_i32_e32 v106, v106
	v_cvt_f32_i32_e32 v101, v101
	v_cvt_f32_i32_e32 v100, v100
	v_cvt_f32_i32_e32 v97, v97
	v_cvt_f32_i32_e32 v96, v96
	v_cvt_f32_i32_e32 v99, v99
	v_cvt_f32_i32_e32 v98, v98
	v_cvt_f32_i32_e32 v93, v93
	v_cvt_f32_i32_e32 v92, v92
	v_cvt_f32_i32_e32 v89, v89
	v_cvt_f32_i32_e32 v88, v88
	v_cvt_f32_i32_e32 v91, v91
	v_cvt_f32_i32_e32 v90, v90
	v_cvt_f32_i32_e32 v85, v85
	v_cvt_f32_i32_e32 v84, v84
	v_cvt_f32_i32_e32 v81, v81
	v_cvt_f32_i32_e32 v80, v80
	v_cvt_f32_i32_e32 v83, v83
	v_cvt_f32_i32_e32 v82, v82
	v_cvt_f32_i32_e32 v77, v77
	v_cvt_f32_i32_e32 v76, v76
	v_cvt_f32_i32_e32 v73, v73
	v_cvt_f32_i32_e32 v72, v72
	v_cvt_f32_i32_e32 v75, v75
	v_cvt_f32_i32_e32 v74, v74
	v_cvt_f32_i32_e32 v69, v69
	v_cvt_f32_i32_e32 v68, v68
	v_cvt_f32_i32_e32 v65, v65
	v_cvt_f32_i32_e32 v64, v64
	v_cvt_f32_i32_e32 v67, v67
	v_cvt_f32_i32_e32 v66, v66
	v_cvt_f32_i32_e32 v45, v45
	v_cvt_f32_i32_e32 v44, v44
	v_cvt_f32_i32_e32 v41, v41
	v_cvt_f32_i32_e32 v40, v40
	v_cvt_f32_i32_e32 v43, v43
	v_cvt_f32_i32_e32 v42, v42
	v_cvt_f32_i32_e32 v37, v37
	v_cvt_f32_i32_e32 v36, v36
	v_cvt_f32_i32_e32 v33, v33
	v_cvt_f32_i32_e32 v32, v32
	v_cvt_f32_i32_e32 v35, v35
	v_cvt_f32_i32_e32 v34, v34
	v_cvt_f32_i32_e32 v29, v29
	v_cvt_f32_i32_e32 v28, v28
	s_waitcnt vmcnt(0)
	v_pk_mul_f32 v[178:179], v[60:61], v[170:171] op_sel_hi:[1,0]
	v_cvt_f32_i32_e32 v25, v25
	v_pk_mul_f32 v[140:141], v[178:179], v[140:141]
	v_cvt_f32_i32_e32 v24, v24
	v_mul_f32_e32 v167, 0xbfb8aa3b, v140
	v_exp_f32_e32 v167, v167
	v_cvt_f32_i32_e32 v27, v27
	v_cvt_f32_i32_e32 v26, v26
	v_cvt_f32_i32_e32 v21, v21
	v_add_f32_e32 v167, 1.0, v167
	v_rcp_f32_e32 v178, v167
	v_mul_f32_e32 v167, 0xbfb8aa3b, v141
	v_exp_f32_e32 v167, v167
	v_cvt_f32_i32_e32 v20, v20
	v_cvt_f32_i32_e32 v17, v17
	v_cvt_f32_i32_e32 v16, v16
	v_add_f32_e32 v167, 1.0, v167
	v_rcp_f32_e32 v179, v167
	v_cvt_f32_i32_e32 v19, v19
	v_cvt_f32_i32_e32 v18, v18
	v_cvt_f32_i32_e32 v13, v13
	v_pk_mul_f32 v[140:141], v[140:141], v[178:179]
	v_pk_mul_f32 v[178:179], v[56:57], v[170:171] op_sel_hi:[1,0]
	v_cvt_f32_i32_e32 v12, v12
	v_pk_mul_f32 v[136:137], v[178:179], v[136:137]
	v_cvt_f32_i32_e32 v9, v9
	v_pk_mul_f32 v[136:137], v[136:137], v[140:141]
	v_cvt_f32_i32_e32 v141, v143
	v_cvt_f32_i32_e32 v140, v142
	v_pk_mul_f32 v[142:143], v[62:63], v[170:171] op_sel_hi:[1,0]
	v_cvt_f32_i32_e32 v8, v8
	v_cvt_f32_i32_e32 v11, v11
	v_pk_mul_f32 v[140:141], v[142:143], v[140:141]
	v_cvt_f32_i32_e32 v10, v10
	v_mul_f32_e32 v142, 0xbfb8aa3b, v140
	v_mul_f32_e32 v143, 0xbfb8aa3b, v141
	v_exp_f32_e32 v142, v142
	v_exp_f32_e32 v143, v143
	v_cvt_f32_i32_e32 v5, v5
	v_cvt_f32_i32_e32 v4, v4
	v_add_f32_e32 v142, 1.0, v142
	v_add_f32_e32 v143, 1.0, v143
	v_rcp_f32_e32 v142, v142
	v_rcp_f32_e32 v143, v143
	v_cvt_f32_i32_e32 v1, v1
	v_cvt_f32_i32_e32 v0, v0
	v_cvt_f32_i32_e32 v3, v3
	v_pk_mul_f32 v[140:141], v[140:141], v[142:143]
	v_pk_mul_f32 v[142:143], v[58:59], v[170:171] op_sel_hi:[1,0]
	v_cvt_f32_i32_e32 v2, v2
	v_pk_mul_f32 v[138:139], v[142:143], v[138:139]
	s_andn2_b64 vcc, exec, s[42:43]
	v_pk_mul_f32 v[138:139], v[138:139], v[140:141]
	v_pk_mul_f32 v[140:141], v[52:53], v[170:171] op_sel_hi:[1,0]
	v_readlane_b32 s45, v251, 9
	v_pk_mul_f32 v[132:133], v[140:141], v[132:133]
	v_readlane_b32 s46, v251, 10
	v_mul_f32_e32 v140, 0xbfb8aa3b, v132
	v_mul_f32_e32 v141, 0xbfb8aa3b, v133
	v_exp_f32_e32 v140, v140
	v_exp_f32_e32 v141, v141
	v_readlane_b32 s47, v251, 11
	v_readlane_b32 s48, v251, 12
	v_add_f32_e32 v140, 1.0, v140
	v_add_f32_e32 v141, 1.0, v141
	v_rcp_f32_e32 v140, v140
	v_rcp_f32_e32 v141, v141
	v_readlane_b32 s49, v251, 13
	v_pk_mul_f32 v[132:133], v[132:133], v[140:141]
	v_pk_mul_f32 v[140:141], v[48:49], v[170:171] op_sel_hi:[1,0]
	s_nop 0
	v_pk_mul_f32 v[128:129], v[140:141], v[128:129]
	s_nop 0
	v_pk_mul_f32 v[128:129], v[128:129], v[132:133]
	v_cvt_f32_i32_e32 v133, v135
	v_cvt_f32_i32_e32 v132, v134
	v_pk_mul_f32 v[134:135], v[54:55], v[170:171] op_sel_hi:[1,0]
	s_nop 0
	v_pk_mul_f32 v[132:133], v[134:135], v[132:133]
	s_nop 0
	v_mul_f32_e32 v134, 0xbfb8aa3b, v132
	v_mul_f32_e32 v135, 0xbfb8aa3b, v133
	v_exp_f32_e32 v134, v134
	v_exp_f32_e32 v135, v135
	v_add_f32_e32 v134, 1.0, v134
	v_add_f32_e32 v135, 1.0, v135
	v_rcp_f32_e32 v134, v134
	v_rcp_f32_e32 v135, v135
	s_nop 0
	v_pk_mul_f32 v[132:133], v[132:133], v[134:135]
	v_pk_mul_f32 v[134:135], v[50:51], v[170:171] op_sel_hi:[1,0]
	s_nop 0
	v_pk_mul_f32 v[130:131], v[134:135], v[130:131]
	s_nop 0
	v_pk_mul_f32 v[134:135], v[130:131], v[132:133]
	v_cvt_pk_bf16_f32 v132, v128, v129
	v_mov_b64_e32 v[128:129], s[24:25]
	v_cvt_pk_bf16_f32 v133, v134, v135
	v_mad_i64_i32 v[134:135], s[24:25], v166, s37, v[128:129]
	v_lshl_add_u64 v[134:135], v[134:135], 0, s[22:23]
	v_lshl_add_u64 v[134:135], v[134:135], 0, s[0:1]
	v_cvt_pk_bf16_f32 v130, v136, v137
	v_cvt_pk_bf16_f32 v131, v138, v139
	v_lshl_add_u64 v[134:135], v[134:135], 0, v[156:157]
	global_store_dwordx4 v[134:135], v[130:133], off
	s_nop 1
	v_mov_b32_e32 v130, v200
	s_nop 0
	v_or_b32_e32 v131, 16, v166
	v_pk_mul_f32 v[132:133], v[60:61], v[130:131] op_sel_hi:[1,0]
	s_nop 0
	v_pk_mul_f32 v[124:125], v[132:133], v[124:125]
	s_nop 0
	v_mul_f32_e32 v132, 0xbfb8aa3b, v124
	v_mul_f32_e32 v133, 0xbfb8aa3b, v125
	v_exp_f32_e32 v132, v132
	v_exp_f32_e32 v133, v133
	v_add_f32_e32 v132, 1.0, v132
	v_add_f32_e32 v133, 1.0, v133
	v_rcp_f32_e32 v132, v132
	v_rcp_f32_e32 v133, v133
	s_nop 0
	v_pk_mul_f32 v[124:125], v[124:125], v[132:133]
	v_pk_mul_f32 v[132:133], v[56:57], v[130:131] op_sel_hi:[1,0]
	s_nop 0
	v_pk_mul_f32 v[120:121], v[132:133], v[120:121]
	s_nop 0
	v_pk_mul_f32 v[120:121], v[120:121], v[124:125]
	v_cvt_f32_i32_e32 v125, v127
	v_cvt_f32_i32_e32 v124, v126
	v_pk_mul_f32 v[126:127], v[62:63], v[130:131] op_sel_hi:[1,0]
	s_nop 0
	v_pk_mul_f32 v[124:125], v[126:127], v[124:125]
	s_nop 0
	v_mul_f32_e32 v126, 0xbfb8aa3b, v124
	v_mul_f32_e32 v127, 0xbfb8aa3b, v125
	v_exp_f32_e32 v126, v126
	v_exp_f32_e32 v127, v127
	v_add_f32_e32 v126, 1.0, v126
	v_add_f32_e32 v127, 1.0, v127
	v_rcp_f32_e32 v126, v126
	v_rcp_f32_e32 v127, v127
	s_nop 0
	v_pk_mul_f32 v[124:125], v[124:125], v[126:127]
	v_pk_mul_f32 v[126:127], v[58:59], v[130:131] op_sel_hi:[1,0]
	s_nop 0
	v_pk_mul_f32 v[122:123], v[126:127], v[122:123]
	s_nop 0
	v_pk_mul_f32 v[122:123], v[122:123], v[124:125]
	v_pk_mul_f32 v[124:125], v[52:53], v[130:131] op_sel_hi:[1,0]
	s_nop 0
	v_pk_mul_f32 v[116:117], v[124:125], v[116:117]
	s_nop 0
	v_mul_f32_e32 v124, 0xbfb8aa3b, v116
	v_mul_f32_e32 v125, 0xbfb8aa3b, v117
	v_exp_f32_e32 v124, v124
	v_exp_f32_e32 v125, v125
	v_add_f32_e32 v124, 1.0, v124
	v_add_f32_e32 v125, 1.0, v125
	v_rcp_f32_e32 v124, v124
	v_rcp_f32_e32 v125, v125
	s_nop 0
	v_pk_mul_f32 v[116:117], v[116:117], v[124:125]
	v_pk_mul_f32 v[124:125], v[48:49], v[130:131] op_sel_hi:[1,0]
	s_nop 0
	v_pk_mul_f32 v[112:113], v[124:125], v[112:113]
	s_nop 0
	v_pk_mul_f32 v[116:117], v[112:113], v[116:117]
	v_cvt_f32_i32_e32 v113, v119
	v_cvt_f32_i32_e32 v112, v118
	v_pk_mul_f32 v[118:119], v[54:55], v[130:131] op_sel_hi:[1,0]
	s_nop 0
	v_pk_mul_f32 v[112:113], v[118:119], v[112:113]
	s_nop 0
	v_mul_f32_e32 v118, 0xbfb8aa3b, v112
	v_mul_f32_e32 v119, 0xbfb8aa3b, v113
	v_exp_f32_e32 v118, v118
	v_exp_f32_e32 v119, v119
	v_add_f32_e32 v118, 1.0, v118
	v_add_f32_e32 v119, 1.0, v119
	v_rcp_f32_e32 v118, v118
	v_rcp_f32_e32 v119, v119
	s_nop 0
	v_pk_mul_f32 v[112:113], v[112:113], v[118:119]
	v_pk_mul_f32 v[118:119], v[50:51], v[130:131] op_sel_hi:[1,0]
	s_nop 0
	v_pk_mul_f32 v[114:115], v[118:119], v[114:115]
	s_nop 0
	v_pk_mul_f32 v[118:119], v[114:115], v[112:113]
	v_cvt_pk_bf16_f32 v114, v116, v117
	v_mad_i64_i32 v[116:117], s[24:25], v131, s37, v[128:129]
	v_lshl_add_u64 v[116:117], v[116:117], 0, s[22:23]
	v_lshl_add_u64 v[116:117], v[116:117], 0, s[0:1]
	v_cvt_pk_bf16_f32 v112, v120, v121
	v_cvt_pk_bf16_f32 v113, v122, v123
	v_cvt_pk_bf16_f32 v115, v118, v119
	v_lshl_add_u64 v[116:117], v[116:117], 0, v[156:157]
	global_store_dwordx4 v[116:117], v[112:115], off
	s_nop 1
	v_mov_b32_e32 v112, v201
	s_nop 0
	v_or_b32_e32 v113, 32, v166
	v_pk_mul_f32 v[114:115], v[60:61], v[112:113] op_sel_hi:[1,0]
	s_nop 0
	v_pk_mul_f32 v[108:109], v[114:115], v[108:109]
	s_nop 0
	v_mul_f32_e32 v114, 0xbfb8aa3b, v108
	v_mul_f32_e32 v115, 0xbfb8aa3b, v109
	v_exp_f32_e32 v114, v114
	v_exp_f32_e32 v115, v115
	v_add_f32_e32 v114, 1.0, v114
	v_add_f32_e32 v115, 1.0, v115
	v_rcp_f32_e32 v114, v114
	v_rcp_f32_e32 v115, v115
	s_nop 0
	v_pk_mul_f32 v[108:109], v[108:109], v[114:115]
	v_pk_mul_f32 v[114:115], v[56:57], v[112:113] op_sel_hi:[1,0]
	s_nop 0
	v_pk_mul_f32 v[104:105], v[114:115], v[104:105]
	s_nop 0
	v_pk_mul_f32 v[104:105], v[104:105], v[108:109]
	v_cvt_f32_i32_e32 v109, v111
	v_cvt_f32_i32_e32 v108, v110
	v_pk_mul_f32 v[110:111], v[62:63], v[112:113] op_sel_hi:[1,0]
	s_nop 0
	v_pk_mul_f32 v[108:109], v[110:111], v[108:109]
	s_nop 0
	v_mul_f32_e32 v110, 0xbfb8aa3b, v108
	v_mul_f32_e32 v111, 0xbfb8aa3b, v109
	v_exp_f32_e32 v110, v110
	v_exp_f32_e32 v111, v111
	v_add_f32_e32 v110, 1.0, v110
	v_add_f32_e32 v111, 1.0, v111
	v_rcp_f32_e32 v110, v110
	v_rcp_f32_e32 v111, v111
	s_nop 0
	v_pk_mul_f32 v[108:109], v[108:109], v[110:111]
	v_pk_mul_f32 v[110:111], v[58:59], v[112:113] op_sel_hi:[1,0]
	s_nop 0
	v_pk_mul_f32 v[106:107], v[110:111], v[106:107]
	s_nop 0
	v_pk_mul_f32 v[106:107], v[106:107], v[108:109]
	v_pk_mul_f32 v[108:109], v[52:53], v[112:113] op_sel_hi:[1,0]
	s_nop 0
	v_pk_mul_f32 v[100:101], v[108:109], v[100:101]
	s_nop 0
	v_mul_f32_e32 v108, 0xbfb8aa3b, v100
	v_mul_f32_e32 v109, 0xbfb8aa3b, v101
	v_exp_f32_e32 v108, v108
	v_exp_f32_e32 v109, v109
	v_add_f32_e32 v108, 1.0, v108
	v_add_f32_e32 v109, 1.0, v109
	v_rcp_f32_e32 v108, v108
	v_rcp_f32_e32 v109, v109
	s_nop 0
	v_pk_mul_f32 v[100:101], v[100:101], v[108:109]
	v_pk_mul_f32 v[108:109], v[48:49], v[112:113] op_sel_hi:[1,0]
	s_nop 0
	v_pk_mul_f32 v[96:97], v[108:109], v[96:97]
	s_nop 0
	v_pk_mul_f32 v[100:101], v[96:97], v[100:101]
	v_cvt_f32_i32_e32 v97, v103
	v_cvt_f32_i32_e32 v96, v102
	v_pk_mul_f32 v[102:103], v[54:55], v[112:113] op_sel_hi:[1,0]
	s_nop 0
	v_pk_mul_f32 v[96:97], v[102:103], v[96:97]
	s_nop 0
	v_mul_f32_e32 v102, 0xbfb8aa3b, v96
	v_mul_f32_e32 v103, 0xbfb8aa3b, v97
	v_exp_f32_e32 v102, v102
	v_exp_f32_e32 v103, v103
	v_add_f32_e32 v102, 1.0, v102
	v_add_f32_e32 v103, 1.0, v103
	v_rcp_f32_e32 v102, v102
	v_rcp_f32_e32 v103, v103
	s_nop 0
	v_pk_mul_f32 v[96:97], v[96:97], v[102:103]
	v_pk_mul_f32 v[102:103], v[50:51], v[112:113] op_sel_hi:[1,0]
	s_nop 0
	v_pk_mul_f32 v[98:99], v[102:103], v[98:99]
	s_nop 0
	v_pk_mul_f32 v[102:103], v[98:99], v[96:97]
	v_cvt_pk_bf16_f32 v98, v100, v101
	v_mad_i64_i32 v[100:101], s[24:25], v113, s37, v[128:129]
	v_lshl_add_u64 v[100:101], v[100:101], 0, s[22:23]
	v_lshl_add_u64 v[100:101], v[100:101], 0, s[0:1]
	v_cvt_pk_bf16_f32 v96, v104, v105
	v_cvt_pk_bf16_f32 v97, v106, v107
	v_cvt_pk_bf16_f32 v99, v102, v103
	v_lshl_add_u64 v[100:101], v[100:101], 0, v[156:157]
	global_store_dwordx4 v[100:101], v[96:99], off
	s_nop 1
	v_mov_b32_e32 v96, v202
	s_nop 0
	v_or_b32_e32 v97, 48, v166
	v_pk_mul_f32 v[98:99], v[60:61], v[96:97] op_sel_hi:[1,0]
	s_nop 0
	v_pk_mul_f32 v[92:93], v[98:99], v[92:93]
	s_nop 0
	v_mul_f32_e32 v98, 0xbfb8aa3b, v92
	v_mul_f32_e32 v99, 0xbfb8aa3b, v93
	v_exp_f32_e32 v98, v98
	v_exp_f32_e32 v99, v99
	v_add_f32_e32 v98, 1.0, v98
	v_add_f32_e32 v99, 1.0, v99
	v_rcp_f32_e32 v98, v98
	v_rcp_f32_e32 v99, v99
	s_nop 0
	v_pk_mul_f32 v[92:93], v[92:93], v[98:99]
	v_pk_mul_f32 v[98:99], v[56:57], v[96:97] op_sel_hi:[1,0]
	s_nop 0
	v_pk_mul_f32 v[88:89], v[98:99], v[88:89]
	s_nop 0
	v_pk_mul_f32 v[88:89], v[88:89], v[92:93]
	v_cvt_f32_i32_e32 v93, v95
	v_cvt_f32_i32_e32 v92, v94
	v_pk_mul_f32 v[94:95], v[62:63], v[96:97] op_sel_hi:[1,0]
	s_nop 0
	v_pk_mul_f32 v[92:93], v[94:95], v[92:93]
	s_nop 0
	v_mul_f32_e32 v94, 0xbfb8aa3b, v92
	v_mul_f32_e32 v95, 0xbfb8aa3b, v93
	v_exp_f32_e32 v94, v94
	v_exp_f32_e32 v95, v95
	v_add_f32_e32 v94, 1.0, v94
	v_add_f32_e32 v95, 1.0, v95
	v_rcp_f32_e32 v94, v94
	v_rcp_f32_e32 v95, v95
	s_nop 0
	v_pk_mul_f32 v[92:93], v[92:93], v[94:95]
	v_pk_mul_f32 v[94:95], v[58:59], v[96:97] op_sel_hi:[1,0]
	s_nop 0
	v_pk_mul_f32 v[90:91], v[94:95], v[90:91]
	s_nop 0
	v_pk_mul_f32 v[90:91], v[90:91], v[92:93]
	v_pk_mul_f32 v[92:93], v[52:53], v[96:97] op_sel_hi:[1,0]
	s_nop 0
	v_pk_mul_f32 v[84:85], v[92:93], v[84:85]
	s_nop 0
	v_mul_f32_e32 v92, 0xbfb8aa3b, v84
	v_mul_f32_e32 v93, 0xbfb8aa3b, v85
	v_exp_f32_e32 v92, v92
	v_exp_f32_e32 v93, v93
	v_add_f32_e32 v92, 1.0, v92
	v_add_f32_e32 v93, 1.0, v93
	v_rcp_f32_e32 v92, v92
	v_rcp_f32_e32 v93, v93
	s_nop 0
	v_pk_mul_f32 v[84:85], v[84:85], v[92:93]
	v_pk_mul_f32 v[92:93], v[48:49], v[96:97] op_sel_hi:[1,0]
	s_nop 0
	v_pk_mul_f32 v[80:81], v[92:93], v[80:81]
	s_nop 0
	v_pk_mul_f32 v[84:85], v[80:81], v[84:85]
	v_cvt_f32_i32_e32 v81, v87
	v_cvt_f32_i32_e32 v80, v86
	v_pk_mul_f32 v[86:87], v[54:55], v[96:97] op_sel_hi:[1,0]
	s_nop 0
	v_pk_mul_f32 v[80:81], v[86:87], v[80:81]
	s_nop 0
	v_mul_f32_e32 v86, 0xbfb8aa3b, v80
	v_mul_f32_e32 v87, 0xbfb8aa3b, v81
	v_exp_f32_e32 v86, v86
	v_exp_f32_e32 v87, v87
	v_add_f32_e32 v86, 1.0, v86
	v_add_f32_e32 v87, 1.0, v87
	v_rcp_f32_e32 v86, v86
	v_rcp_f32_e32 v87, v87
	s_nop 0
	v_pk_mul_f32 v[80:81], v[80:81], v[86:87]
	v_pk_mul_f32 v[86:87], v[50:51], v[96:97] op_sel_hi:[1,0]
	s_nop 0
	v_pk_mul_f32 v[82:83], v[86:87], v[82:83]
	s_nop 0
	v_pk_mul_f32 v[86:87], v[82:83], v[80:81]
	v_cvt_pk_bf16_f32 v82, v84, v85
	v_mad_i64_i32 v[84:85], s[24:25], v97, s37, v[128:129]
	v_lshl_add_u64 v[84:85], v[84:85], 0, s[22:23]
	v_lshl_add_u64 v[84:85], v[84:85], 0, s[0:1]
	v_cvt_pk_bf16_f32 v80, v88, v89
	v_cvt_pk_bf16_f32 v81, v90, v91
	v_cvt_pk_bf16_f32 v83, v86, v87
	v_lshl_add_u64 v[84:85], v[84:85], 0, v[156:157]
	global_store_dwordx4 v[84:85], v[80:83], off
	s_nop 1
	v_mov_b32_e32 v80, v203
	s_nop 0
	v_add_u32_e32 v81, 0x80, v166
	v_pk_mul_f32 v[82:83], v[60:61], v[80:81] op_sel_hi:[1,0]
	s_nop 0
	v_pk_mul_f32 v[76:77], v[82:83], v[76:77]
	s_nop 0
	v_mul_f32_e32 v82, 0xbfb8aa3b, v76
	v_mul_f32_e32 v83, 0xbfb8aa3b, v77
	v_exp_f32_e32 v82, v82
	v_exp_f32_e32 v83, v83
	v_add_f32_e32 v82, 1.0, v82
	v_add_f32_e32 v83, 1.0, v83
	v_rcp_f32_e32 v82, v82
	v_rcp_f32_e32 v83, v83
	s_nop 0
	v_pk_mul_f32 v[76:77], v[76:77], v[82:83]
	v_pk_mul_f32 v[82:83], v[56:57], v[80:81] op_sel_hi:[1,0]
	s_nop 0
	v_pk_mul_f32 v[72:73], v[82:83], v[72:73]
	s_nop 0
	v_pk_mul_f32 v[72:73], v[72:73], v[76:77]
	v_cvt_f32_i32_e32 v77, v79
	v_cvt_f32_i32_e32 v76, v78
	v_pk_mul_f32 v[78:79], v[62:63], v[80:81] op_sel_hi:[1,0]
	s_nop 0
	v_pk_mul_f32 v[76:77], v[78:79], v[76:77]
	s_nop 0
	v_mul_f32_e32 v78, 0xbfb8aa3b, v76
	v_mul_f32_e32 v79, 0xbfb8aa3b, v77
	v_exp_f32_e32 v78, v78
	v_exp_f32_e32 v79, v79
	v_add_f32_e32 v78, 1.0, v78
	v_add_f32_e32 v79, 1.0, v79
	v_rcp_f32_e32 v78, v78
	v_rcp_f32_e32 v79, v79
	s_nop 0
	v_pk_mul_f32 v[76:77], v[76:77], v[78:79]
	v_pk_mul_f32 v[78:79], v[58:59], v[80:81] op_sel_hi:[1,0]
	s_nop 0
	v_pk_mul_f32 v[74:75], v[78:79], v[74:75]
	s_nop 0
	v_pk_mul_f32 v[74:75], v[74:75], v[76:77]
	v_pk_mul_f32 v[76:77], v[52:53], v[80:81] op_sel_hi:[1,0]
	s_nop 0
	v_pk_mul_f32 v[68:69], v[76:77], v[68:69]
	s_nop 0
	v_mul_f32_e32 v76, 0xbfb8aa3b, v68
	v_mul_f32_e32 v77, 0xbfb8aa3b, v69
	v_exp_f32_e32 v76, v76
	v_exp_f32_e32 v77, v77
	v_add_f32_e32 v76, 1.0, v76
	v_add_f32_e32 v77, 1.0, v77
	v_rcp_f32_e32 v76, v76
	v_rcp_f32_e32 v77, v77
	s_nop 0
	v_pk_mul_f32 v[68:69], v[68:69], v[76:77]
	v_pk_mul_f32 v[76:77], v[48:49], v[80:81] op_sel_hi:[1,0]
	s_nop 0
	v_pk_mul_f32 v[64:65], v[76:77], v[64:65]
	s_nop 0
	v_pk_mul_f32 v[68:69], v[64:65], v[68:69]
	v_cvt_f32_i32_e32 v65, v71
	v_cvt_f32_i32_e32 v64, v70
	v_pk_mul_f32 v[70:71], v[54:55], v[80:81] op_sel_hi:[1,0]
	s_nop 0
	v_pk_mul_f32 v[64:65], v[70:71], v[64:65]
	s_nop 0
	v_mul_f32_e32 v70, 0xbfb8aa3b, v64
	v_mul_f32_e32 v71, 0xbfb8aa3b, v65
	v_exp_f32_e32 v70, v70
	v_exp_f32_e32 v71, v71
	v_add_f32_e32 v70, 1.0, v70
	v_add_f32_e32 v71, 1.0, v71
	v_rcp_f32_e32 v70, v70
	v_rcp_f32_e32 v71, v71
	s_nop 0
	v_pk_mul_f32 v[64:65], v[64:65], v[70:71]
	v_pk_mul_f32 v[70:71], v[50:51], v[80:81] op_sel_hi:[1,0]
	s_nop 0
	v_pk_mul_f32 v[66:67], v[70:71], v[66:67]
	s_nop 0
	v_pk_mul_f32 v[70:71], v[66:67], v[64:65]
	v_cvt_pk_bf16_f32 v66, v68, v69
	v_mad_i64_i32 v[68:69], s[24:25], v81, s37, v[128:129]
	v_lshl_add_u64 v[68:69], v[68:69], 0, s[22:23]
	v_lshl_add_u64 v[68:69], v[68:69], 0, s[0:1]
	v_cvt_pk_bf16_f32 v64, v72, v73
	v_cvt_pk_bf16_f32 v65, v74, v75
	v_cvt_pk_bf16_f32 v67, v70, v71
	v_lshl_add_u64 v[68:69], v[68:69], 0, v[156:157]
	global_store_dwordx4 v[68:69], v[64:67], off
	s_nop 1
	v_mov_b32_e32 v64, v204
	s_nop 0
	v_add_u32_e32 v65, 0x90, v166
	v_pk_mul_f32 v[66:67], v[60:61], v[64:65] op_sel_hi:[1,0]
	s_nop 0
	v_pk_mul_f32 v[44:45], v[66:67], v[44:45]
	s_nop 0
	v_mul_f32_e32 v66, 0xbfb8aa3b, v44
	v_mul_f32_e32 v67, 0xbfb8aa3b, v45
	v_exp_f32_e32 v66, v66
	v_exp_f32_e32 v67, v67
	v_add_f32_e32 v66, 1.0, v66
	v_add_f32_e32 v67, 1.0, v67
	v_rcp_f32_e32 v66, v66
	v_rcp_f32_e32 v67, v67
	s_nop 0
	v_pk_mul_f32 v[44:45], v[44:45], v[66:67]
	v_pk_mul_f32 v[66:67], v[56:57], v[64:65] op_sel_hi:[1,0]
	s_nop 0
	v_pk_mul_f32 v[40:41], v[66:67], v[40:41]
	s_nop 0
	v_pk_mul_f32 v[40:41], v[40:41], v[44:45]
	v_cvt_f32_i32_e32 v45, v47
	v_cvt_f32_i32_e32 v44, v46
	v_pk_mul_f32 v[46:47], v[62:63], v[64:65] op_sel_hi:[1,0]
	s_nop 0
	v_pk_mul_f32 v[44:45], v[46:47], v[44:45]
	s_nop 0
	v_mul_f32_e32 v46, 0xbfb8aa3b, v44
	v_mul_f32_e32 v47, 0xbfb8aa3b, v45
	v_exp_f32_e32 v46, v46
	v_exp_f32_e32 v47, v47
	v_add_f32_e32 v46, 1.0, v46
	v_add_f32_e32 v47, 1.0, v47
	v_rcp_f32_e32 v46, v46
	v_rcp_f32_e32 v47, v47
	s_nop 0
	v_pk_mul_f32 v[44:45], v[44:45], v[46:47]
	v_pk_mul_f32 v[46:47], v[58:59], v[64:65] op_sel_hi:[1,0]
	s_nop 0
	v_pk_mul_f32 v[42:43], v[46:47], v[42:43]
	s_nop 0
	v_pk_mul_f32 v[42:43], v[42:43], v[44:45]
	v_pk_mul_f32 v[44:45], v[52:53], v[64:65] op_sel_hi:[1,0]
	s_nop 0
	v_pk_mul_f32 v[36:37], v[44:45], v[36:37]
	s_nop 0
	v_mul_f32_e32 v44, 0xbfb8aa3b, v36
	v_mul_f32_e32 v45, 0xbfb8aa3b, v37
	v_exp_f32_e32 v44, v44
	v_exp_f32_e32 v45, v45
	v_add_f32_e32 v44, 1.0, v44
	v_add_f32_e32 v45, 1.0, v45
	v_rcp_f32_e32 v44, v44
	v_rcp_f32_e32 v45, v45
	s_nop 0
	v_pk_mul_f32 v[36:37], v[36:37], v[44:45]
	v_pk_mul_f32 v[44:45], v[48:49], v[64:65] op_sel_hi:[1,0]
	s_nop 0
	v_pk_mul_f32 v[32:33], v[44:45], v[32:33]
	s_nop 0
	v_pk_mul_f32 v[36:37], v[32:33], v[36:37]
	v_cvt_f32_i32_e32 v33, v39
	v_cvt_f32_i32_e32 v32, v38
	v_pk_mul_f32 v[38:39], v[54:55], v[64:65] op_sel_hi:[1,0]
	s_nop 0
	v_pk_mul_f32 v[32:33], v[38:39], v[32:33]
	s_nop 0
	v_mul_f32_e32 v38, 0xbfb8aa3b, v32
	v_mul_f32_e32 v39, 0xbfb8aa3b, v33
	v_exp_f32_e32 v38, v38
	v_exp_f32_e32 v39, v39
	v_add_f32_e32 v38, 1.0, v38
	v_add_f32_e32 v39, 1.0, v39
	v_rcp_f32_e32 v38, v38
	v_rcp_f32_e32 v39, v39
	s_nop 0
	v_pk_mul_f32 v[32:33], v[32:33], v[38:39]
	v_pk_mul_f32 v[38:39], v[50:51], v[64:65] op_sel_hi:[1,0]
	s_nop 0
	v_pk_mul_f32 v[34:35], v[38:39], v[34:35]
	s_nop 0
	v_pk_mul_f32 v[38:39], v[34:35], v[32:33]
	v_cvt_pk_bf16_f32 v34, v36, v37
	v_mad_i64_i32 v[36:37], s[24:25], v65, s37, v[128:129]
	v_lshl_add_u64 v[36:37], v[36:37], 0, s[22:23]
	v_lshl_add_u64 v[36:37], v[36:37], 0, s[0:1]
	v_cvt_pk_bf16_f32 v32, v40, v41
	v_cvt_pk_bf16_f32 v33, v42, v43
	v_cvt_pk_bf16_f32 v35, v38, v39
	v_lshl_add_u64 v[36:37], v[36:37], 0, v[156:157]
	global_store_dwordx4 v[36:37], v[32:35], off
	s_nop 1
	v_mov_b32_e32 v32, v205
	s_nop 0
	v_add_u32_e32 v33, 0xa0, v166
	v_pk_mul_f32 v[34:35], v[60:61], v[32:33] op_sel_hi:[1,0]
	s_nop 0
	v_pk_mul_f32 v[28:29], v[34:35], v[28:29]
	s_nop 0
	v_mul_f32_e32 v34, 0xbfb8aa3b, v28
	v_mul_f32_e32 v35, 0xbfb8aa3b, v29
	v_exp_f32_e32 v34, v34
	v_exp_f32_e32 v35, v35
	v_add_f32_e32 v34, 1.0, v34
	v_add_f32_e32 v35, 1.0, v35
	v_rcp_f32_e32 v34, v34
	v_rcp_f32_e32 v35, v35
	s_nop 0
	v_pk_mul_f32 v[28:29], v[28:29], v[34:35]
	v_pk_mul_f32 v[34:35], v[56:57], v[32:33] op_sel_hi:[1,0]
	s_nop 0
	v_pk_mul_f32 v[24:25], v[34:35], v[24:25]
	s_nop 0
	v_pk_mul_f32 v[24:25], v[24:25], v[28:29]
	v_cvt_f32_i32_e32 v29, v31
	v_cvt_f32_i32_e32 v28, v30
	v_pk_mul_f32 v[30:31], v[62:63], v[32:33] op_sel_hi:[1,0]
	s_nop 0
	v_pk_mul_f32 v[28:29], v[30:31], v[28:29]
	s_nop 0
	v_mul_f32_e32 v30, 0xbfb8aa3b, v28
	v_mul_f32_e32 v31, 0xbfb8aa3b, v29
	v_exp_f32_e32 v30, v30
	v_exp_f32_e32 v31, v31
	v_add_f32_e32 v30, 1.0, v30
	v_add_f32_e32 v31, 1.0, v31
	v_rcp_f32_e32 v30, v30
	v_rcp_f32_e32 v31, v31
	s_nop 0
	v_pk_mul_f32 v[28:29], v[28:29], v[30:31]
	v_pk_mul_f32 v[30:31], v[58:59], v[32:33] op_sel_hi:[1,0]
	s_nop 0
	v_pk_mul_f32 v[26:27], v[30:31], v[26:27]
	s_nop 0
	v_pk_mul_f32 v[26:27], v[26:27], v[28:29]
	v_pk_mul_f32 v[28:29], v[52:53], v[32:33] op_sel_hi:[1,0]
	s_nop 0
	v_pk_mul_f32 v[20:21], v[28:29], v[20:21]
	s_nop 0
	v_mul_f32_e32 v28, 0xbfb8aa3b, v20
	v_mul_f32_e32 v29, 0xbfb8aa3b, v21
	v_exp_f32_e32 v28, v28
	v_exp_f32_e32 v29, v29
	v_add_f32_e32 v28, 1.0, v28
	v_add_f32_e32 v29, 1.0, v29
	v_rcp_f32_e32 v28, v28
	v_rcp_f32_e32 v29, v29
	s_nop 0
	v_pk_mul_f32 v[20:21], v[20:21], v[28:29]
	v_pk_mul_f32 v[28:29], v[48:49], v[32:33] op_sel_hi:[1,0]
	s_nop 0
	v_pk_mul_f32 v[16:17], v[28:29], v[16:17]
	s_nop 0
	v_pk_mul_f32 v[20:21], v[16:17], v[20:21]
	v_cvt_f32_i32_e32 v17, v23
	v_cvt_f32_i32_e32 v16, v22
	v_pk_mul_f32 v[22:23], v[54:55], v[32:33] op_sel_hi:[1,0]
	s_nop 0
	v_pk_mul_f32 v[16:17], v[22:23], v[16:17]
	s_nop 0
	v_mul_f32_e32 v22, 0xbfb8aa3b, v16
	v_mul_f32_e32 v23, 0xbfb8aa3b, v17
	v_exp_f32_e32 v22, v22
	v_exp_f32_e32 v23, v23
	v_add_f32_e32 v22, 1.0, v22
	v_add_f32_e32 v23, 1.0, v23
	v_rcp_f32_e32 v22, v22
	v_rcp_f32_e32 v23, v23
	s_nop 0
	v_pk_mul_f32 v[16:17], v[16:17], v[22:23]
	v_pk_mul_f32 v[22:23], v[50:51], v[32:33] op_sel_hi:[1,0]
	s_nop 0
	v_pk_mul_f32 v[18:19], v[22:23], v[18:19]
	s_nop 0
	v_pk_mul_f32 v[22:23], v[18:19], v[16:17]
	v_cvt_pk_bf16_f32 v18, v20, v21
	v_mad_i64_i32 v[20:21], s[24:25], v33, s37, v[128:129]
	v_lshl_add_u64 v[20:21], v[20:21], 0, s[22:23]
	v_lshl_add_u64 v[20:21], v[20:21], 0, s[0:1]
	v_cvt_pk_bf16_f32 v16, v24, v25
	v_cvt_pk_bf16_f32 v17, v26, v27
	v_cvt_pk_bf16_f32 v19, v22, v23
	v_lshl_add_u64 v[20:21], v[20:21], 0, v[156:157]
	global_store_dwordx4 v[20:21], v[16:19], off
	s_nop 1
	v_mov_b32_e32 v16, v206
	s_nop 0
	v_add_u32_e32 v17, 0xb0, v166
	v_pk_mul_f32 v[18:19], v[60:61], v[16:17] op_sel_hi:[1,0]
	s_nop 0
	v_pk_mul_f32 v[12:13], v[18:19], v[12:13]
	s_nop 0
	v_mul_f32_e32 v18, 0xbfb8aa3b, v12
	v_mul_f32_e32 v19, 0xbfb8aa3b, v13
	v_exp_f32_e32 v18, v18
	v_exp_f32_e32 v19, v19
	v_add_f32_e32 v18, 1.0, v18
	v_add_f32_e32 v19, 1.0, v19
	v_rcp_f32_e32 v18, v18
	v_rcp_f32_e32 v19, v19
	s_nop 0
	v_pk_mul_f32 v[12:13], v[12:13], v[18:19]
	v_pk_mul_f32 v[18:19], v[56:57], v[16:17] op_sel_hi:[1,0]
	s_nop 0
	v_pk_mul_f32 v[8:9], v[18:19], v[8:9]
	s_nop 0
	v_pk_mul_f32 v[8:9], v[8:9], v[12:13]
	v_cvt_f32_i32_e32 v13, v15
	v_cvt_f32_i32_e32 v12, v14
	v_pk_mul_f32 v[14:15], v[62:63], v[16:17] op_sel_hi:[1,0]
	s_nop 0
	v_pk_mul_f32 v[12:13], v[14:15], v[12:13]
	s_nop 0
	v_mul_f32_e32 v14, 0xbfb8aa3b, v12
	v_mul_f32_e32 v15, 0xbfb8aa3b, v13
	v_exp_f32_e32 v14, v14
	v_exp_f32_e32 v15, v15
	v_add_f32_e32 v14, 1.0, v14
	v_add_f32_e32 v15, 1.0, v15
	v_rcp_f32_e32 v14, v14
	v_rcp_f32_e32 v15, v15
	s_nop 0
	v_pk_mul_f32 v[12:13], v[12:13], v[14:15]
	v_pk_mul_f32 v[14:15], v[58:59], v[16:17] op_sel_hi:[1,0]
	s_nop 0
	v_pk_mul_f32 v[10:11], v[14:15], v[10:11]
	s_nop 0
	v_pk_mul_f32 v[10:11], v[10:11], v[12:13]
	v_pk_mul_f32 v[12:13], v[52:53], v[16:17] op_sel_hi:[1,0]
	s_nop 0
	v_pk_mul_f32 v[4:5], v[12:13], v[4:5]
	s_nop 0
	v_mul_f32_e32 v12, 0xbfb8aa3b, v4
	v_mul_f32_e32 v13, 0xbfb8aa3b, v5
	v_exp_f32_e32 v12, v12
	v_exp_f32_e32 v13, v13
	v_add_f32_e32 v12, 1.0, v12
	v_add_f32_e32 v13, 1.0, v13
	v_rcp_f32_e32 v12, v12
	v_rcp_f32_e32 v13, v13
	s_nop 0
	v_pk_mul_f32 v[4:5], v[4:5], v[12:13]
	v_pk_mul_f32 v[12:13], v[48:49], v[16:17] op_sel_hi:[1,0]
	s_nop 0
	v_pk_mul_f32 v[0:1], v[12:13], v[0:1]
	s_nop 0
	v_pk_mul_f32 v[4:5], v[0:1], v[4:5]
	v_cvt_f32_i32_e32 v1, v7
	v_cvt_f32_i32_e32 v0, v6
	v_pk_mul_f32 v[6:7], v[54:55], v[16:17] op_sel_hi:[1,0]
	s_nop 0
	v_pk_mul_f32 v[0:1], v[6:7], v[0:1]
	s_nop 0
	v_mul_f32_e32 v6, 0xbfb8aa3b, v0
	v_mul_f32_e32 v7, 0xbfb8aa3b, v1
	v_exp_f32_e32 v6, v6
	v_exp_f32_e32 v7, v7
	v_add_f32_e32 v6, 1.0, v6
	v_add_f32_e32 v7, 1.0, v7
	v_rcp_f32_e32 v6, v6
	v_rcp_f32_e32 v7, v7
	s_nop 0
	v_pk_mul_f32 v[0:1], v[0:1], v[6:7]
	v_pk_mul_f32 v[6:7], v[50:51], v[16:17] op_sel_hi:[1,0]
	s_nop 0
	v_pk_mul_f32 v[2:3], v[6:7], v[2:3]
	s_nop 0
	v_pk_mul_f32 v[6:7], v[2:3], v[0:1]
	v_cvt_pk_bf16_f32 v2, v4, v5
	v_mad_i64_i32 v[4:5], s[24:25], v17, s37, v[128:129]
	v_lshl_add_u64 v[4:5], v[4:5], 0, s[22:23]
	v_lshl_add_u64 v[4:5], v[4:5], 0, s[0:1]
	v_cvt_pk_bf16_f32 v0, v8, v9
	v_cvt_pk_bf16_f32 v1, v10, v11
	v_cvt_pk_bf16_f32 v3, v6, v7
	v_lshl_add_u64 v[4:5], v[4:5], 0, v[156:157]
	s_mov_b64 s[22:23], -1
	global_store_dwordx4 v[4:5], v[0:3], off
	s_cbranch_vccnz .LBB0_1962
	s_andn2_b64 vcc, exec, s[2:3]
	s_cbranch_vccnz .LBB0_1961
	s_barrier
	s_branch .LBB0_1961
